# retention intra-chunk phase: K fragments of the score MFMAs loaded up to 11 ahead, GroupNorm gain loads hoisted out of the 16-step store ladder (counted vmcnt instead of vmcnt(0) per step)
# speedup vs baseline: 1.0029x; 1.0029x over previous
; __device__ __forceinline__ void phase_r3(bf16_t* P1, const bf16_t* ST, const bf16_t* CT, const float* dfw, const float* dbw, const float* gn, uchar* lds, bool with_ctx, bool nostore = false) {
;     ...
;         const float lgf = -expf(dfw[h]) * LOG2E, lgb = -expf(dbw[h]) * LOG2E;
;         bf16_t* qp = P1 + (size_t)rows0 * P1W + h * 64; const bf16_t* kp = qp + 512; bf16_t* vp = P1 + (size_t)rows0 * P1W + 1024 + h * 128;
; #pragma unroll
;         for (int i = 0; i < 4; ++i) { const int task = tg + 256 * i, pa = task >> 4, c8 = task & 15;
;             const u32x4 r0 = *(const u32x4*)(vp + (size_t)(2 * pa) * P1W + 8 * c8), r1 = *(const u32x4*)(vp + (size_t)(2 * pa + 1) * P1W + 8 * c8);
;             tstore_pair(Tv, TS, (2 * pa & 64) + pos64(2 * pa & 63), c8, r0, r1, c8); }
;         __syncthreads();
.LBB0_1198:
	s_or_b64 exec, exec, s[4:5]
	v_lshlrev_b64 v[4:5], 2, v[0:1]
	v_lshl_add_u64 v[6:7], s[36:37], 0, v[4:5]
	global_load_dword v3, v[6:7], off
	s_mov_b32 s4, 0x3fb8aa3b
	s_mov_b32 s5, 0xc2ce8ed0
	s_mov_b32 s8, 0x42b17218
	v_lshl_add_u64 v[4:5], s[80:81], 0, v[4:5]
	v_lshlrev_b32_e32 v0, 7, v0
	v_mov_b32_e32 v95, v1
	v_mov_b32_e32 v97, v1
	v_mov_b32_e32 v99, v1
	v_mov_b32_e32 v101, v1
	s_waitcnt vmcnt(0)
	v_mul_f32_e32 v6, 0x3fb8aa3b, v3
	v_fma_f32 v7, v3, s4, -v6
	v_rndne_f32_e32 v8, v6
	v_fmac_f32_e32 v7, 0x32a5705f, v3
	v_sub_f32_e32 v6, v6, v8
	v_add_f32_e32 v6, v6, v7
	v_exp_f32_e32 v6, v6
	v_cvt_i32_f32_e32 v7, v8
	v_cmp_ngt_f32_e32 vcc, s5, v3
	v_ldexp_f32 v6, v6, v7
	s_nop 0
	v_cndmask_b32_e32 v6, 0, v6, vcc
	v_cmp_nlt_f32_e32 vcc, s8, v3
	global_load_dword v3, v[4:5], off
	s_waitcnt vmcnt(0)
	v_mul_f32_e32 v4, 0x3fb8aa3b, v3
	v_cndmask_b32_e32 v108, v218, v6, vcc
	v_fma_f32 v5, v3, s4, -v4
	v_rndne_f32_e32 v6, v4
	v_fmac_f32_e32 v5, 0x32a5705f, v3
	v_sub_f32_e32 v4, v4, v6
	v_add_f32_e32 v4, v4, v5
	v_exp_f32_e32 v4, v4
	v_cvt_i32_f32_e32 v5, v6
	v_cmp_ngt_f32_e32 vcc, s5, v3
	v_ldexp_f32 v4, v4, v5
	s_nop 0
	v_cndmask_b32_e32 v4, 0, v4, vcc
	v_cmp_nlt_f32_e32 vcc, s8, v3
	s_nop 1
	v_cndmask_b32_e32 v12, v218, v4, vcc
	v_mov_b64_e32 v[4:5], s[30:31]
	v_mad_i64_i32 v[2:3], s[4:5], v2, s16, v[4:5]
	v_lshl_add_u64 v[102:103], v[0:1], 1, v[2:3]
	v_lshl_add_u64 v[10:11], v[2:3], 0, v[0:1]
	v_lshl_add_u64 v[2:3], v[102:103], 0, v[94:95]
	v_lshl_add_u64 v[6:7], v[2:3], 0, v[96:97]
	s_movk_i32 s4, 0x1000
	v_add_co_u32_e32 v8, vcc, s4, v6
	global_load_dwordx4 v[2:5], v[6:7], off offset:2048
	s_nop 0
	v_addc_co_u32_e32 v9, vcc, 0, v7, vcc
	global_load_dwordx4 v[14:17], v[8:9], off offset:3584
	s_mov_b32 s4, 0x2c000
	v_mov_b32_e32 v95, v85
	v_mul_f32_e32 v97, 0xbfb8aa3b, v12
	s_waitcnt vmcnt(1)
	v_and_b32_e32 v8, 0xffff, v2
	v_lshrrev_b32_e32 v2, 16, v2
	s_waitcnt vmcnt(0)
	v_lshl_or_b32 v8, v14, 16, v8
	v_and_or_b32 v2, v14, s62, v2
	ds_write2_b32 v89, v8, v2 offset1:68
	v_and_b32_e32 v2, 0xffff, v3
	v_lshrrev_b32_e32 v3, 16, v3
	v_lshl_or_b32 v2, v15, 16, v2
	v_and_or_b32 v3, v15, s62, v3
	ds_write2_b32 v89, v2, v3 offset0:136 offset1:204
	v_and_b32_e32 v2, 0xffff, v4
	v_lshrrev_b32_e32 v3, 16, v4
	v_lshl_or_b32 v2, v16, 16, v2
	v_and_or_b32 v3, v16, s62, v3
	v_add_u32_e32 v4, 0x400, v89
	ds_write2_b32 v4, v2, v3 offset0:16 offset1:84
	v_and_b32_e32 v2, 0xffff, v5
	v_lshrrev_b32_e32 v3, 16, v5
	v_lshl_or_b32 v2, v17, 16, v2
	v_and_or_b32 v3, v17, s62, v3
	ds_write2_b32 v4, v2, v3 offset0:152 offset1:220
	v_add_co_u32_e32 v2, vcc, s4, v6
	s_mov_b32 s4, 0x2d000
	s_nop 0
	v_addc_co_u32_e32 v3, vcc, 0, v7, vcc
	v_add_co_u32_e32 v8, vcc, s4, v6
	global_load_dwordx4 v[2:5], v[2:3], off offset:2048
	s_nop 0
	v_addc_co_u32_e32 v9, vcc, 0, v7, vcc
	global_load_dwordx4 v[14:17], v[8:9], off offset:3584
	s_mov_b32 s4, 0x58000
	s_waitcnt vmcnt(1)
	v_and_b32_e32 v8, 0xffff, v2
	v_lshrrev_b32_e32 v2, 16, v2
	s_waitcnt vmcnt(0)
	v_lshl_or_b32 v8, v14, 16, v8
	v_and_or_b32 v2, v14, s62, v2
	ds_write2_b32 v91, v8, v2 offset1:68
	v_and_b32_e32 v2, 0xffff, v3
	v_lshrrev_b32_e32 v3, 16, v3
	v_lshl_or_b32 v2, v15, 16, v2
	v_and_or_b32 v3, v15, s62, v3
	ds_write2_b32 v91, v2, v3 offset0:136 offset1:204
	v_and_b32_e32 v2, 0xffff, v4
	v_lshrrev_b32_e32 v3, 16, v4
	v_lshl_or_b32 v2, v16, 16, v2
	v_and_or_b32 v3, v16, s62, v3
	v_add_u32_e32 v4, 0x400, v91
	ds_write2_b32 v4, v2, v3 offset0:16 offset1:84
	v_and_b32_e32 v2, 0xffff, v5
	v_lshrrev_b32_e32 v3, 16, v5
	v_lshl_or_b32 v2, v17, 16, v2
	v_and_or_b32 v3, v17, s62, v3
	ds_write2_b32 v4, v2, v3 offset0:152 offset1:220
	v_add_co_u32_e32 v2, vcc, s4, v6
	s_mov_b32 s4, 0x59000
	s_nop 0
	v_addc_co_u32_e32 v3, vcc, 0, v7, vcc
	v_add_co_u32_e32 v8, vcc, s4, v6
	global_load_dwordx4 v[2:5], v[2:3], off offset:2048
	s_nop 0
	v_addc_co_u32_e32 v9, vcc, 0, v7, vcc
	global_load_dwordx4 v[14:17], v[8:9], off offset:3584
	s_mov_b32 s4, 0x84000
	s_waitcnt vmcnt(1)
	v_and_b32_e32 v8, 0xffff, v2
	v_lshrrev_b32_e32 v2, 16, v2
	s_waitcnt vmcnt(0)
	v_lshl_or_b32 v8, v14, 16, v8
	v_and_or_b32 v2, v14, s62, v2
	ds_write2_b32 v164, v8, v2 offset1:68
	v_and_b32_e32 v2, 0xffff, v3
	v_lshrrev_b32_e32 v3, 16, v3
	v_lshl_or_b32 v2, v15, 16, v2
	v_and_or_b32 v3, v15, s62, v3
	ds_write2_b32 v164, v2, v3 offset0:136 offset1:204
	v_and_b32_e32 v2, 0xffff, v4
	v_lshrrev_b32_e32 v3, 16, v4
	v_lshl_or_b32 v2, v16, 16, v2
	v_and_or_b32 v3, v16, s62, v3
	v_add_u32_e32 v4, 0x400, v164
	ds_write2_b32 v4, v2, v3 offset0:16 offset1:84
	v_and_b32_e32 v2, 0xffff, v5
	v_lshrrev_b32_e32 v3, 16, v5
	v_lshl_or_b32 v2, v17, 16, v2
	v_and_or_b32 v3, v17, s62, v3
	ds_write2_b32 v4, v2, v3 offset0:152 offset1:220
	v_add_co_u32_e32 v2, vcc, s4, v6
	s_mov_b32 s4, 0x85000
	s_nop 0
	v_addc_co_u32_e32 v3, vcc, 0, v7, vcc
	v_add_co_u32_e32 v6, vcc, s4, v6
	global_load_dwordx4 v[2:5], v[2:3], off offset:2048
	s_nop 0
	v_addc_co_u32_e32 v7, vcc, 0, v7, vcc
	global_load_dwordx4 v[6:9], v[6:7], off offset:3584
	s_waitcnt vmcnt(1)
	v_and_b32_e32 v13, 0xffff, v2
	v_lshrrev_b32_e32 v2, 16, v2
	s_waitcnt vmcnt(0)
	v_lshl_or_b32 v13, v6, 16, v13
	v_and_or_b32 v2, v6, s62, v2
	ds_write2_b32 v165, v13, v2 offset1:68
	v_and_b32_e32 v2, 0xffff, v3
	v_lshrrev_b32_e32 v3, 16, v3
	v_lshl_or_b32 v2, v7, 16, v2
	v_and_or_b32 v3, v7, s62, v3
	ds_write2_b32 v165, v2, v3 offset0:136 offset1:204
	v_and_b32_e32 v2, 0xffff, v4
	v_lshrrev_b32_e32 v3, 16, v4
	v_lshl_or_b32 v2, v8, 16, v2
	v_and_or_b32 v3, v8, s62, v3
	v_add_u32_e32 v4, 0x400, v165
	ds_write2_b32 v4, v2, v3 offset0:16 offset1:84
	v_and_b32_e32 v2, 0xffff, v5
	v_lshrrev_b32_e32 v3, 16, v5
	v_lshl_or_b32 v2, v9, 16, v2
	v_and_or_b32 v3, v9, s62, v3
	ds_write2_b32 v4, v2, v3 offset0:152 offset1:220
	s_waitcnt lgkmcnt(0)
	s_barrier
; __device__ __forceinline__ float ex2(float x) { return __builtin_amdgcn_exp2f(x); }
; #define MFMA32(a, b, c) __builtin_amdgcn_mfma_f32_32x32x16_bf16((a), (b), (c), 0, 0, 0)
; __device__ __forceinline__ void phase_r3(bf16_t* P1, const bf16_t* ST, const bf16_t* CT, const float* dfw, const float* dbw, const float* gn, uchar* lds, bool with_ctx, bool nostore = false) {
;     ...
;         int il_ = ib * 32 + l32; asm volatile("" : "+v"(il_)); const int il = il_;
;         bf16x8 qf[4];
; #pragma unroll
;         for (int s = 0; s < 4; ++s) qf[s] = *(const bf16x8*)(qp + (size_t)il * P1W + 16 * s + 8 * hi);
;         f32x16 sT[4];
; #pragma unroll
;         for (int jb = 0; jb < 4; ++jb) { sT[jb] = (f32x16){};
; #pragma unroll
;             for (int s = 0; s < 4; ++s) { const bf16x8 kf = *(const bf16x8*)(kp + (size_t)(jb * 32 + l32) * P1W + 16 * s + 8 * hi); sT[jb] = MFMA32(kf, qf[s], sT[jb]); }
;             if (jb & 1) asm volatile("" ::: "memory"); }
;         const float fdl = (float)(il - 4 * hi);
; #pragma unroll
;         for (int jb = 0; jb < 4; ++jb)
; #pragma unroll
;             for (int r = 0; r < 16; ++r) { const float fd = fdl - (float)(jb * 32 + (r & 3) + 8 * (r >> 2));
;                 const float e = ex2(fd * (fd > 0.f ? lgf : -lgb)); sT[jb][r] *= (fd == 0.f ? 2.f : e); }
	s_nop 0
	v_mad_i64_i32 v[2:3], s[4:5], v95, s16, v[10:11]
	v_lshl_add_u64 v[2:3], v[2:3], 0, v[98:99]
	global_load_dwordx4 v[78:81], v[2:3], off
	global_load_dwordx4 v[74:77], v[2:3], off offset:32
	global_load_dwordx4 v[70:73], v[2:3], off offset:64
	global_load_dwordx4 v[66:69], v[2:3], off offset:96
	v_lshl_add_u64 v[2:3], v[10:11], 0, v[98:99]
	v_lshl_add_u64 v[6:7], v[2:3], 0, v[100:101]
	s_mov_b64 s[4:5], 0x2c000
	v_lshl_add_u64 v[8:9], v[6:7], 0, s[4:5]
	s_mov_b64 s[4:5], 0x58000
	v_lshl_add_u64 v[248:249], v[6:7], 0, s[4:5]
	s_mov_b64 s[4:5], 0x84000
	v_lshl_add_u64 v[114:115], v[6:7], 0, s[4:5]
	global_load_dwordx4 v[194:197], v[6:7], off offset:1024
	global_load_dwordx4 v[198:201], v[6:7], off offset:1056
	global_load_dwordx4 v[202:205], v[6:7], off offset:1088
	global_load_dwordx4 v[212:215], v[6:7], off offset:1120
	global_load_dwordx4 v[220:223], v[8:9], off offset:1024
	global_load_dwordx4 v[224:227], v[8:9], off offset:1056
	global_load_dwordx4 v[228:231], v[8:9], off offset:1088
	global_load_dwordx4 v[232:235], v[8:9], off offset:1120
	global_load_dwordx4 v[236:239], v[248:249], off offset:1024
	global_load_dwordx4 v[240:243], v[248:249], off offset:1056
	global_load_dwordx4 v[244:247], v[248:249], off offset:1088
	v_mul_f32_e32 v101, 0xbfb8aa3b, v108
	v_sub_u32_e32 v108, v95, v82
	v_cmp_lt_i32_e32 vcc, 0, v108
	s_mov_b32 s4, 0xc2200000
	s_mov_b32 s5, 0xc2240000
	s_waitcnt vmcnt(10)
	v_mfma_f32_32x32x16_bf16 v[50:65], v[194:197], v[78:81], 0
	global_load_dwordx4 v[194:197], v[248:249], off offset:1120
	s_waitcnt vmcnt(10)
	v_mfma_f32_32x32x16_bf16 v[50:65], v[198:201], v[74:77], v[50:65]
	global_load_dwordx4 v[198:201], v[114:115], off offset:1024
	s_waitcnt vmcnt(10)
	v_mfma_f32_32x32x16_bf16 v[50:65], v[202:205], v[70:73], v[50:65]
	global_load_dwordx4 v[202:205], v[114:115], off offset:1056
	s_waitcnt vmcnt(10)
	v_mfma_f32_32x32x16_bf16 v[50:65], v[212:215], v[66:69], v[50:65]
	global_load_dwordx4 v[212:215], v[114:115], off offset:1088
	s_waitcnt vmcnt(10)
	v_mfma_f32_32x32x16_bf16 v[34:49], v[220:223], v[78:81], 0
	global_load_dwordx4 v[220:223], v[114:115], off offset:1120
	s_waitcnt vmcnt(10)
	v_mfma_f32_32x32x16_bf16 v[34:49], v[224:227], v[74:77], v[34:49]
	s_waitcnt vmcnt(9)
	v_mfma_f32_32x32x16_bf16 v[34:49], v[228:231], v[70:73], v[34:49]
	s_waitcnt vmcnt(8)
	v_mfma_f32_32x32x16_bf16 v[34:49], v[232:235], v[66:69], v[34:49]
	s_waitcnt vmcnt(7)
	v_mfma_f32_32x32x16_bf16 v[18:33], v[236:239], v[78:81], 0
	s_waitcnt vmcnt(6)
	v_mfma_f32_32x32x16_bf16 v[18:33], v[240:243], v[74:77], v[18:33]
	s_waitcnt vmcnt(5)
	v_mfma_f32_32x32x16_bf16 v[18:33], v[244:247], v[70:73], v[18:33]
	s_waitcnt vmcnt(4)
	v_mfma_f32_32x32x16_bf16 v[18:33], v[194:197], v[66:69], v[18:33]
	s_waitcnt vmcnt(3)
	v_mfma_f32_32x32x16_bf16 v[2:17], v[198:201], v[78:81], 0
	s_waitcnt vmcnt(2)
	v_mfma_f32_32x32x16_bf16 v[2:17], v[202:205], v[74:77], v[2:17]
	s_waitcnt vmcnt(1)
	v_mfma_f32_32x32x16_bf16 v[2:17], v[212:215], v[70:73], v[2:17]
	v_cvt_f32_i32_e32 v114, v108
	v_cndmask_b32_e64 v108, -v97, v101, vcc
	v_cmp_ne_u32_e32 vcc, v95, v82
	v_mul_f32_e32 v108, v108, v114
	v_exp_f32_e32 v108, v108
	s_waitcnt vmcnt(0)
	v_mfma_f32_32x32x16_bf16 v[2:17], v[220:223], v[66:69], v[2:17]
	v_cndmask_b32_e32 v108, 2.0, v108, vcc
	v_mul_f32_e32 v167, v108, v50
	v_add_f32_e32 v50, -1.0, v114
	v_cmp_lt_f32_e32 vcc, 0, v50
	s_nop 1
	v_cndmask_b32_e64 v108, -v97, v101, vcc
	v_mul_f32_e32 v108, v50, v108
	v_exp_f32_e32 v108, v108
	v_cmp_neq_f32_e32 vcc, 0, v50
	s_nop 1
	v_cndmask_b32_e32 v50, 2.0, v108, vcc
	v_mul_f32_e32 v168, v50, v51
	v_pk_add_f32 v[50:51], v[114:115], s[18:19] op_sel_hi:[0,1]
	v_cmp_lt_f32_e32 vcc, 0, v50
	s_nop 1
	v_cndmask_b32_e64 v108, -v97, v101, vcc
	v_cmp_lt_f32_e32 vcc, 0, v51
	v_mul_f32_e32 v108, v50, v108
	v_exp_f32_e32 v108, v108
	v_cndmask_b32_e64 v109, -v97, v101, vcc
	v_mul_f32_e32 v109, v51, v109
	v_exp_f32_e32 v109, v109
	v_cmp_neq_f32_e32 vcc, 0, v51
	s_nop 1
	v_cndmask_b32_e32 v51, 2.0, v109, vcc
	v_cmp_neq_f32_e32 vcc, 0, v50
	s_nop 1
	v_cndmask_b32_e32 v50, 2.0, v108, vcc
	v_pk_mul_f32 v[50:51], v[50:51], v[52:53]
	v_pk_add_f32 v[52:53], v[114:115], s[22:23] op_sel_hi:[0,1]
	v_cmp_lt_f32_e32 vcc, 0, v52
	s_nop 1
	v_cndmask_b32_e64 v108, -v97, v101, vcc
	v_cmp_lt_f32_e32 vcc, 0, v53
	v_mul_f32_e32 v108, v52, v108
	v_exp_f32_e32 v108, v108
	v_cndmask_b32_e64 v109, -v97, v101, vcc
	v_mul_f32_e32 v109, v53, v109
	v_exp_f32_e32 v109, v109
	v_cmp_neq_f32_e32 vcc, 0, v53
	s_nop 1
	v_cndmask_b32_e32 v53, 2.0, v109, vcc
	v_cmp_neq_f32_e32 vcc, 0, v52
	s_nop 1
	v_cndmask_b32_e32 v52, 2.0, v108, vcc
	v_pk_mul_f32 v[52:53], v[52:53], v[54:55]
	v_pk_add_f32 v[54:55], v[114:115], s[26:27] op_sel_hi:[0,1]
	v_cmp_lt_f32_e32 vcc, 0, v54
	s_nop 1
	v_cndmask_b32_e64 v108, -v97, v101, vcc
	v_cmp_lt_f32_e32 vcc, 0, v55
	v_mul_f32_e32 v108, v54, v108
	v_exp_f32_e32 v108, v108
	v_cndmask_b32_e64 v109, -v97, v101, vcc
	v_mul_f32_e32 v109, v55, v109
	v_exp_f32_e32 v109, v109
	v_cmp_neq_f32_e32 vcc, 0, v55
	s_nop 1
	v_cndmask_b32_e32 v55, 2.0, v109, vcc
	v_cmp_neq_f32_e32 vcc, 0, v54
	s_nop 1
	v_cndmask_b32_e32 v54, 2.0, v108, vcc
	v_pk_mul_f32 v[54:55], v[54:55], v[56:57]
	v_pk_add_f32 v[56:57], v[114:115], s[28:29] op_sel_hi:[0,1]
	v_cmp_lt_f32_e32 vcc, 0, v56
	s_nop 1
	v_cndmask_b32_e64 v108, -v97, v101, vcc
	v_cmp_lt_f32_e32 vcc, 0, v57
	v_mul_f32_e32 v108, v56, v108
	v_exp_f32_e32 v108, v108
	v_cndmask_b32_e64 v109, -v97, v101, vcc
	v_mul_f32_e32 v109, v57, v109
	v_exp_f32_e32 v109, v109
	v_cmp_neq_f32_e32 vcc, 0, v57
	s_nop 1
	v_cndmask_b32_e32 v57, 2.0, v109, vcc
	v_cmp_neq_f32_e32 vcc, 0, v56
	s_nop 1
	v_cndmask_b32_e32 v56, 2.0, v108, vcc
; __device__ __forceinline__ float ex2(float x) { return __builtin_amdgcn_exp2f(x); }
; __device__ __forceinline__ void phase_r3(bf16_t* P1, const bf16_t* ST, const bf16_t* CT, const float* dfw, const float* dbw, const float* gn, uchar* lds, bool with_ctx, bool nostore = false) {
;     ...
;         const float fdl = (float)(il - 4 * hi);
; #pragma unroll
;         for (int jb = 0; jb < 4; ++jb)
; #pragma unroll
;             for (int r = 0; r < 16; ++r) { const float fd = fdl - (float)(jb * 32 + (r & 3) + 8 * (r >> 2));
;                 const float e = ex2(fd * (fd > 0.f ? lgf : -lgb)); sT[jb][r] *= (fd == 0.f ? 2.f : e); }
;         f32x16 oT[4] = {};
; #pragma unroll
;         for (int kk = 0; kk < 8; ++kk) {
;             const int jb = kk >> 1, r0 = 8 * (kk & 1);
;             const bf16x8 pf = pack8(sT[jb][r0], sT[jb][r0 + 1], sT[jb][r0 + 2], sT[jb][r0 + 3], sT[jb][r0 + 4], sT[jb][r0 + 5], sT[jb][r0 + 6], sT[jb][r0 + 7]);
	v_pk_mul_f32 v[128:129], v[56:57], v[58:59]
	v_pk_add_f32 v[56:57], v[114:115], s[42:43] op_sel_hi:[0,1]
	v_cmp_lt_f32_e32 vcc, 0, v56
	v_cvt_pk_bf16_f32 v184, v128, v129
	s_nop 0
	v_cndmask_b32_e64 v58, -v97, v101, vcc
	v_cmp_lt_f32_e32 vcc, 0, v57
	v_mul_f32_e32 v58, v56, v58
	v_exp_f32_e32 v58, v58
	v_cndmask_b32_e64 v59, -v97, v101, vcc
	v_mul_f32_e32 v59, v57, v59
	v_exp_f32_e32 v59, v59
	v_cmp_neq_f32_e32 vcc, 0, v57
	s_nop 1
	v_cndmask_b32_e32 v57, 2.0, v59, vcc
	v_cmp_neq_f32_e32 vcc, 0, v56
	s_nop 1
	v_cndmask_b32_e32 v56, 2.0, v58, vcc
	v_pk_mul_f32 v[140:141], v[56:57], v[60:61]
	v_pk_add_f32 v[56:57], v[114:115], s[44:45] op_sel_hi:[0,1]
	v_cmp_lt_f32_e32 vcc, 0, v56
	v_cvt_pk_bf16_f32 v185, v140, v141
	s_nop 0
	v_cndmask_b32_e64 v58, -v97, v101, vcc
	v_cmp_lt_f32_e32 vcc, 0, v57
	v_mul_f32_e32 v58, v56, v58
	v_exp_f32_e32 v58, v58
	v_cndmask_b32_e64 v59, -v97, v101, vcc
	v_mul_f32_e32 v59, v57, v59
	v_exp_f32_e32 v59, v59
	v_cmp_neq_f32_e32 vcc, 0, v57
	s_nop 1
	v_cndmask_b32_e32 v57, 2.0, v59, vcc
	v_cmp_neq_f32_e32 vcc, 0, v56
	s_nop 1
	v_cndmask_b32_e32 v56, 2.0, v58, vcc
	v_pk_mul_f32 v[148:149], v[56:57], v[62:63]
	v_pk_add_f32 v[56:57], v[114:115], s[46:47] op_sel_hi:[0,1]
	v_cmp_lt_f32_e32 vcc, 0, v56
	v_cvt_pk_bf16_f32 v186, v148, v149
	s_nop 0
	v_cndmask_b32_e64 v58, -v97, v101, vcc
	v_cmp_lt_f32_e32 vcc, 0, v57
	v_mul_f32_e32 v58, v56, v58
	v_exp_f32_e32 v58, v58
	v_cndmask_b32_e64 v59, -v97, v101, vcc
	v_mul_f32_e32 v59, v57, v59
	v_exp_f32_e32 v59, v59
	v_cmp_neq_f32_e32 vcc, 0, v57
	s_nop 1
	v_cndmask_b32_e32 v57, 2.0, v59, vcc
	v_cmp_neq_f32_e32 vcc, 0, v56
	s_nop 1
	v_cndmask_b32_e32 v56, 2.0, v58, vcc
	v_pk_mul_f32 v[156:157], v[56:57], v[64:65]
	v_pk_add_f32 v[56:57], v[114:115], s[48:49] op_sel_hi:[0,1]
	v_cmp_lt_f32_e32 vcc, 0, v56
	v_cvt_pk_bf16_f32 v187, v156, v157
	s_nop 0
	v_cndmask_b32_e64 v58, -v97, v101, vcc
	v_cmp_lt_f32_e32 vcc, 0, v57
	v_mul_f32_e32 v58, v56, v58
	v_exp_f32_e32 v58, v58
	v_cndmask_b32_e64 v59, -v97, v101, vcc
	v_mul_f32_e32 v59, v57, v59
	v_exp_f32_e32 v59, v59
	v_cmp_neq_f32_e32 vcc, 0, v57
	s_nop 1
	v_cndmask_b32_e32 v57, 2.0, v59, vcc
	v_cmp_neq_f32_e32 vcc, 0, v56
	s_nop 1
	v_cndmask_b32_e32 v56, 2.0, v58, vcc
	v_pk_mul_f32 v[142:143], v[56:57], v[34:35]
	v_pk_add_f32 v[34:35], v[114:115], s[50:51] op_sel_hi:[0,1]
	v_cmp_lt_f32_e32 vcc, 0, v34
	v_cvt_pk_bf16_f32 v140, v142, v143
	s_nop 0
	v_cndmask_b32_e64 v56, -v97, v101, vcc
	v_cmp_lt_f32_e32 vcc, 0, v35
	v_mul_f32_e32 v56, v34, v56
	v_exp_f32_e32 v56, v56
	v_cndmask_b32_e64 v57, -v97, v101, vcc
	v_mul_f32_e32 v57, v35, v57
	v_exp_f32_e32 v57, v57
	v_cmp_neq_f32_e32 vcc, 0, v35
	s_nop 1
	v_cndmask_b32_e32 v35, 2.0, v57, vcc
	v_cmp_neq_f32_e32 vcc, 0, v34
	s_nop 1
	v_cndmask_b32_e32 v34, 2.0, v56, vcc
	v_pk_mul_f32 v[150:151], v[34:35], v[36:37]
	v_pk_add_f32 v[34:35], v[114:115], s[4:5] op_sel_hi:[0,1]
	v_cmp_lt_f32_e32 vcc, 0, v34
	s_mov_b32 s4, 0xc2280000
	s_mov_b32 s5, 0xc22c0000
	v_cndmask_b32_e64 v36, -v97, v101, vcc
	v_cmp_lt_f32_e32 vcc, 0, v35
	v_mul_f32_e32 v36, v34, v36
	v_exp_f32_e32 v36, v36
	v_cndmask_b32_e64 v37, -v97, v101, vcc
	v_mul_f32_e32 v37, v35, v37
	v_exp_f32_e32 v37, v37
	v_cmp_neq_f32_e32 vcc, 0, v35
	v_cvt_pk_bf16_f32 v141, v150, v151
	s_nop 0
	v_cndmask_b32_e32 v35, 2.0, v37, vcc
	v_cmp_neq_f32_e32 vcc, 0, v34
	s_nop 1
	v_cndmask_b32_e32 v34, 2.0, v36, vcc
	v_pk_mul_f32 v[158:159], v[34:35], v[38:39]
	v_pk_add_f32 v[34:35], v[114:115], s[4:5] op_sel_hi:[0,1]
	v_cmp_lt_f32_e32 vcc, 0, v34
	s_mov_b32 s4, 0xc2400000
	s_mov_b32 s5, 0xc2440000
	v_cndmask_b32_e64 v36, -v97, v101, vcc
	v_cmp_lt_f32_e32 vcc, 0, v35
	v_mul_f32_e32 v36, v34, v36
	v_exp_f32_e32 v36, v36
	v_cndmask_b32_e64 v37, -v97, v101, vcc
	v_mul_f32_e32 v37, v35, v37
	v_exp_f32_e32 v37, v37
	v_cmp_neq_f32_e32 vcc, 0, v35
	v_cvt_pk_bf16_f32 v142, v158, v159
	s_nop 0
	v_cndmask_b32_e32 v35, 2.0, v37, vcc
	v_cmp_neq_f32_e32 vcc, 0, v34
	s_nop 1
	v_cndmask_b32_e32 v34, 2.0, v36, vcc
	v_pk_mul_f32 v[162:163], v[34:35], v[40:41]
	v_pk_add_f32 v[34:35], v[114:115], s[4:5] op_sel_hi:[0,1]
	v_cmp_lt_f32_e32 vcc, 0, v34
	s_mov_b32 s4, 0xc2480000
	s_mov_b32 s5, 0xc24c0000
	v_cndmask_b32_e64 v36, -v97, v101, vcc
	v_cmp_lt_f32_e32 vcc, 0, v35
	v_mul_f32_e32 v36, v34, v36
	v_exp_f32_e32 v36, v36
	v_cndmask_b32_e64 v37, -v97, v101, vcc
	v_mul_f32_e32 v37, v35, v37
	v_exp_f32_e32 v37, v37
	v_cmp_neq_f32_e32 vcc, 0, v35
	v_cvt_pk_bf16_f32 v143, v162, v163
	s_nop 0
	v_cndmask_b32_e32 v35, 2.0, v37, vcc
	v_cmp_neq_f32_e32 vcc, 0, v34
	s_nop 1
	v_cndmask_b32_e32 v34, 2.0, v36, vcc
	v_pk_mul_f32 v[126:127], v[34:35], v[42:43]
	v_pk_add_f32 v[34:35], v[114:115], s[4:5] op_sel_hi:[0,1]
	v_cmp_lt_f32_e32 vcc, 0, v34
	s_mov_b32 s4, 0xc2600000
	s_mov_b32 s5, 0xc2640000
	v_cndmask_b32_e64 v36, -v97, v101, vcc
	v_cmp_lt_f32_e32 vcc, 0, v35
	v_mul_f32_e32 v36, v34, v36
	v_exp_f32_e32 v36, v36
	v_cndmask_b32_e64 v37, -v97, v101, vcc
	v_mul_f32_e32 v37, v35, v37
	v_exp_f32_e32 v37, v37
	v_cmp_neq_f32_e32 vcc, 0, v35
	v_cvt_pk_bf16_f32 v126, v126, v127
	s_nop 0
	v_cndmask_b32_e32 v35, 2.0, v37, vcc
	v_cmp_neq_f32_e32 vcc, 0, v34
	s_nop 1
	v_cndmask_b32_e32 v34, 2.0, v36, vcc
	v_pk_mul_f32 v[134:135], v[34:35], v[44:45]
	v_pk_add_f32 v[34:35], v[114:115], s[4:5] op_sel_hi:[0,1]
	v_cmp_lt_f32_e32 vcc, 0, v34
	s_mov_b32 s4, 0xc2680000
	s_mov_b32 s5, 0xc26c0000
	v_cndmask_b32_e64 v36, -v97, v101, vcc
	v_cmp_lt_f32_e32 vcc, 0, v35
	v_mul_f32_e32 v36, v34, v36
	v_exp_f32_e32 v36, v36
	v_cndmask_b32_e64 v37, -v97, v101, vcc
	v_mul_f32_e32 v37, v35, v37
	v_exp_f32_e32 v37, v37
	v_cmp_neq_f32_e32 vcc, 0, v35
	v_cvt_pk_bf16_f32 v127, v134, v135
	s_nop 0
	v_cndmask_b32_e32 v35, 2.0, v37, vcc
; __device__ __forceinline__ float ex2(float x) { return __builtin_amdgcn_exp2f(x); }
; __device__ __forceinline__ void phase_r3(bf16_t* P1, const bf16_t* ST, const bf16_t* CT, const float* dfw, const float* dbw, const float* gn, uchar* lds, bool with_ctx, bool nostore = false) {
;     ...
;         const float fdl = (float)(il - 4 * hi);
; #pragma unroll
;         for (int jb = 0; jb < 4; ++jb)
; #pragma unroll
;             for (int r = 0; r < 16; ++r) { const float fd = fdl - (float)(jb * 32 + (r & 3) + 8 * (r >> 2));
;                 const float e = ex2(fd * (fd > 0.f ? lgf : -lgb)); sT[jb][r] *= (fd == 0.f ? 2.f : e); }
;         f32x16 oT[4] = {};
; #pragma unroll
;         for (int kk = 0; kk < 8; ++kk) {
;             const int jb = kk >> 1, r0 = 8 * (kk & 1);
;             const bf16x8 pf = pack8(sT[jb][r0], sT[jb][r0 + 1], sT[jb][r0 + 2], sT[jb][r0 + 3], sT[jb][r0 + 4], sT[jb][r0 + 5], sT[jb][r0 + 6], sT[jb][r0 + 7]);
	v_cmp_neq_f32_e32 vcc, 0, v34
	s_nop 1
	v_cndmask_b32_e32 v34, 2.0, v36, vcc
	v_pk_mul_f32 v[144:145], v[34:35], v[46:47]
	v_pk_add_f32 v[34:35], v[114:115], s[4:5] op_sel_hi:[0,1]
	v_cmp_lt_f32_e32 vcc, 0, v34
	s_mov_b32 s4, 0xc2800000
	s_mov_b32 s5, 0xc2820000
	v_cndmask_b32_e64 v36, -v97, v101, vcc
	v_cmp_lt_f32_e32 vcc, 0, v35
	v_mul_f32_e32 v36, v34, v36
	v_exp_f32_e32 v36, v36
	v_cndmask_b32_e64 v37, -v97, v101, vcc
	v_mul_f32_e32 v37, v35, v37
	v_exp_f32_e32 v37, v37
	v_cmp_neq_f32_e32 vcc, 0, v35
	v_cvt_pk_bf16_f32 v128, v144, v145
	s_nop 0
	v_cndmask_b32_e32 v35, 2.0, v37, vcc
	v_cmp_neq_f32_e32 vcc, 0, v34
	s_nop 1
	v_cndmask_b32_e32 v34, 2.0, v36, vcc
	v_pk_mul_f32 v[152:153], v[34:35], v[48:49]
	v_pk_add_f32 v[34:35], v[114:115], s[4:5] op_sel_hi:[0,1]
	v_cmp_lt_f32_e32 vcc, 0, v34
	s_mov_b32 s4, 0xc2840000
	s_mov_b32 s5, 0xc2860000
	v_cndmask_b32_e64 v36, -v97, v101, vcc
	v_cmp_lt_f32_e32 vcc, 0, v35
	v_mul_f32_e32 v36, v34, v36
	v_exp_f32_e32 v36, v36
	v_cndmask_b32_e64 v37, -v97, v101, vcc
	v_mul_f32_e32 v37, v35, v37
	v_exp_f32_e32 v37, v37
	v_cmp_neq_f32_e32 vcc, 0, v35
	v_cvt_pk_bf16_f32 v129, v152, v153
	s_nop 0
	v_cndmask_b32_e32 v35, 2.0, v37, vcc
	v_cmp_neq_f32_e32 vcc, 0, v34
	s_nop 1
	v_cndmask_b32_e32 v34, 2.0, v36, vcc
	v_pk_mul_f32 v[138:139], v[34:35], v[18:19]
	v_pk_add_f32 v[18:19], v[114:115], s[4:5] op_sel_hi:[0,1]
	v_cmp_lt_f32_e32 vcc, 0, v18
	s_mov_b32 s4, 0xc2900000
	s_mov_b32 s5, 0xc2920000
	v_cndmask_b32_e64 v34, -v97, v101, vcc
	v_cmp_lt_f32_e32 vcc, 0, v19
	v_mul_f32_e32 v34, v18, v34
	v_exp_f32_e32 v34, v34
	v_cndmask_b32_e64 v35, -v97, v101, vcc
	v_mul_f32_e32 v35, v19, v35
	v_exp_f32_e32 v35, v35
	v_cmp_neq_f32_e32 vcc, 0, v19
	s_nop 1
	v_cndmask_b32_e32 v19, 2.0, v35, vcc
	v_cmp_neq_f32_e32 vcc, 0, v18
	s_nop 1
	v_cndmask_b32_e32 v18, 2.0, v34, vcc
	v_pk_mul_f32 v[146:147], v[18:19], v[20:21]
	v_pk_add_f32 v[18:19], v[114:115], s[4:5] op_sel_hi:[0,1]
	v_cmp_lt_f32_e32 vcc, 0, v18
	s_mov_b32 s4, 0xc2940000
	s_mov_b32 s5, 0xc2960000
	v_cndmask_b32_e64 v20, -v97, v101, vcc
	v_cmp_lt_f32_e32 vcc, 0, v19
	v_mul_f32_e32 v20, v18, v20
	v_exp_f32_e32 v20, v20
	v_cndmask_b32_e64 v21, -v97, v101, vcc
	v_mul_f32_e32 v21, v19, v21
	v_exp_f32_e32 v21, v21
	v_cmp_neq_f32_e32 vcc, 0, v19
	s_nop 1
	v_cndmask_b32_e32 v19, 2.0, v21, vcc
	v_cmp_neq_f32_e32 vcc, 0, v18
	s_nop 1
	v_cndmask_b32_e32 v18, 2.0, v20, vcc
	v_pk_mul_f32 v[154:155], v[18:19], v[22:23]
	v_pk_add_f32 v[18:19], v[114:115], s[4:5] op_sel_hi:[0,1]
	v_cmp_lt_f32_e32 vcc, 0, v18
	s_mov_b32 s4, 0xc2a00000
	s_mov_b32 s5, 0xc2a20000
	v_cndmask_b32_e64 v20, -v97, v101, vcc
	v_cmp_lt_f32_e32 vcc, 0, v19
	v_mul_f32_e32 v20, v18, v20
	v_exp_f32_e32 v20, v20
	v_cndmask_b32_e64 v21, -v97, v101, vcc
	v_mul_f32_e32 v21, v19, v21
	v_exp_f32_e32 v21, v21
	v_cmp_neq_f32_e32 vcc, 0, v19
	s_nop 1
	v_cndmask_b32_e32 v19, 2.0, v21, vcc
	v_cmp_neq_f32_e32 vcc, 0, v18
	s_nop 1
	v_cndmask_b32_e32 v18, 2.0, v20, vcc
	v_pk_mul_f32 v[160:161], v[18:19], v[24:25]
	v_pk_add_f32 v[18:19], v[114:115], s[4:5] op_sel_hi:[0,1]
	v_cmp_lt_f32_e32 vcc, 0, v18
	s_mov_b32 s4, 0xc2a40000
	s_mov_b32 s5, 0xc2a60000
	v_cndmask_b32_e64 v20, -v97, v101, vcc
	v_cmp_lt_f32_e32 vcc, 0, v19
	v_mul_f32_e32 v20, v18, v20
	v_exp_f32_e32 v20, v20
	v_cndmask_b32_e64 v21, -v97, v101, vcc
	v_mul_f32_e32 v21, v19, v21
	v_exp_f32_e32 v21, v21
	v_cmp_neq_f32_e32 vcc, 0, v19
	s_nop 1
	v_cndmask_b32_e32 v19, 2.0, v21, vcc
	v_cmp_neq_f32_e32 vcc, 0, v18
	s_nop 1
	v_cndmask_b32_e32 v18, 2.0, v20, vcc
	v_pk_mul_f32 v[122:123], v[18:19], v[26:27]
	v_pk_add_f32 v[18:19], v[114:115], s[4:5] op_sel_hi:[0,1]
	v_cmp_lt_f32_e32 vcc, 0, v18
	s_mov_b32 s4, 0xc2b00000
	s_mov_b32 s5, 0xc2b20000
	v_cndmask_b32_e64 v20, -v97, v101, vcc
	v_cmp_lt_f32_e32 vcc, 0, v19
	v_mul_f32_e32 v20, v18, v20
	v_exp_f32_e32 v20, v20
	v_cndmask_b32_e64 v21, -v97, v101, vcc
	v_mul_f32_e32 v21, v19, v21
	v_exp_f32_e32 v21, v21
	v_cmp_neq_f32_e32 vcc, 0, v19
	s_nop 1
	v_cndmask_b32_e32 v19, 2.0, v21, vcc
	v_cmp_neq_f32_e32 vcc, 0, v18
	s_nop 1
	v_cndmask_b32_e32 v18, 2.0, v20, vcc
	v_pk_mul_f32 v[130:131], v[18:19], v[28:29]
	v_pk_add_f32 v[18:19], v[114:115], s[4:5] op_sel_hi:[0,1]
	v_cmp_lt_f32_e32 vcc, 0, v18
	s_mov_b32 s4, 0xc2b40000
	s_mov_b32 s5, 0xc2b60000
	v_cndmask_b32_e64 v20, -v97, v101, vcc
	v_cmp_lt_f32_e32 vcc, 0, v19
	v_mul_f32_e32 v20, v18, v20
	v_exp_f32_e32 v20, v20
	v_cndmask_b32_e64 v21, -v97, v101, vcc
	v_mul_f32_e32 v21, v19, v21
	v_exp_f32_e32 v21, v21
	v_cmp_neq_f32_e32 vcc, 0, v19
	s_nop 1
	v_cndmask_b32_e32 v19, 2.0, v21, vcc
	v_cmp_neq_f32_e32 vcc, 0, v18
	s_nop 1
	v_cndmask_b32_e32 v18, 2.0, v20, vcc
	v_pk_mul_f32 v[132:133], v[18:19], v[30:31]
	v_pk_add_f32 v[18:19], v[114:115], s[4:5] op_sel_hi:[0,1]
	v_cmp_lt_f32_e32 vcc, 0, v18
	s_mov_b32 s4, 0xc2c00000
	s_mov_b32 s5, 0xc2c20000
	v_cndmask_b32_e64 v20, -v97, v101, vcc
	v_cmp_lt_f32_e32 vcc, 0, v19
	v_mul_f32_e32 v20, v18, v20
	v_exp_f32_e32 v20, v20
	v_cndmask_b32_e64 v21, -v97, v101, vcc
	v_mul_f32_e32 v21, v19, v21
	v_exp_f32_e32 v21, v21
	v_cmp_neq_f32_e32 vcc, 0, v19
	v_cvt_pk_bf16_f32 v152, v132, v133
	v_lshlrev_b32_e32 v132, 16, v78
	v_cndmask_b32_e32 v19, 2.0, v21, vcc
	v_cmp_neq_f32_e32 vcc, 0, v18
	v_and_b32_e32 v133, 0xffff0000, v78
	v_lshlrev_b32_e32 v78, 1, v86
	v_cndmask_b32_e32 v18, 2.0, v20, vcc
	v_pk_mul_f32 v[136:137], v[18:19], v[32:33]
	v_pk_add_f32 v[18:19], v[114:115], s[4:5] op_sel_hi:[0,1]
	v_cmp_lt_f32_e32 vcc, 0, v18
	s_mov_b32 s4, 0xc2c40000
	s_mov_b32 s5, 0xc2c60000
	v_cndmask_b32_e64 v20, -v97, v101, vcc
	v_cmp_lt_f32_e32 vcc, 0, v19
	v_mul_f32_e32 v20, v18, v20
	v_exp_f32_e32 v20, v20
	v_cndmask_b32_e64 v21, -v97, v101, vcc
; __device__ __forceinline__ float ex2(float x) { return __builtin_amdgcn_exp2f(x); }
; #define MFMA32(a, b, c) __builtin_amdgcn_mfma_f32_32x32x16_bf16((a), (b), (c), 0, 0, 0)
; __device__ __forceinline__ void phase_r3(bf16_t* P1, const bf16_t* ST, const bf16_t* CT, const float* dfw, const float* dbw, const float* gn, uchar* lds, bool with_ctx, bool nostore = false) {
;     ...
;             for (int r = 0; r < 16; ++r) { const float fd = fdl - (float)(jb * 32 + (r & 3) + 8 * (r >> 2));
;                 const float e = ex2(fd * (fd > 0.f ? lgf : -lgb)); sT[jb][r] *= (fd == 0.f ? 2.f : e); }
;         f32x16 oT[4] = {};
; #pragma unroll
;         for (int kk = 0; kk < 8; ++kk) {
;             const int jb = kk >> 1, r0 = 8 * (kk & 1);
;             const bf16x8 pf = pack8(sT[jb][r0], sT[jb][r0 + 1], sT[jb][r0 + 2], sT[jb][r0 + 3], sT[jb][r0 + 4], sT[jb][r0 + 5], sT[jb][r0 + 6], sT[jb][r0 + 7]);
; #pragma unroll
;             for (int dvb = 0; dvb < 4; ++dvb) { const bf16x8 av = *(const bf16x8*)(Tv + (dvb * 32 + l32) * TS + (16 * kk + 8 * hi) * 2); oT[dvb] = MFMA32(av, pf, oT[dvb]); }
;             if (kk & 1) asm volatile("" ::: "memory");
;         }
	v_mul_f32_e32 v21, v19, v21
	v_exp_f32_e32 v21, v21
	v_cmp_neq_f32_e32 vcc, 0, v19
	v_cvt_pk_bf16_f32 v153, v136, v137
	s_nop 0
	v_cndmask_b32_e32 v19, 2.0, v21, vcc
	v_cmp_neq_f32_e32 vcc, 0, v18
	v_cvt_pk_bf16_f32 v21, v54, v55
	s_nop 0
	v_cndmask_b32_e32 v18, 2.0, v20, vcc
	v_pk_mul_f32 v[116:117], v[18:19], v[2:3]
	v_pk_add_f32 v[2:3], v[114:115], s[4:5] op_sel_hi:[0,1]
	v_cmp_lt_f32_e32 vcc, 0, v2
	s_mov_b32 s4, 0xc2d00000
	s_mov_b32 s5, 0xc2d20000
	v_cndmask_b32_e64 v18, -v97, v101, vcc
	v_cmp_lt_f32_e32 vcc, 0, v3
	v_mul_f32_e32 v18, v2, v18
	v_exp_f32_e32 v18, v18
	v_cndmask_b32_e64 v19, -v97, v101, vcc
	v_mul_f32_e32 v19, v3, v19
	v_exp_f32_e32 v19, v19
	v_cmp_neq_f32_e32 vcc, 0, v3
	v_cvt_pk_bf16_f32 v20, v52, v53
	v_cvt_pk_bf16_f32 v116, v116, v117
	v_cndmask_b32_e32 v3, 2.0, v19, vcc
	v_cmp_neq_f32_e32 vcc, 0, v2
	v_cvt_pk_bf16_f32 v19, v50, v51
	s_nop 0
	v_cndmask_b32_e32 v2, 2.0, v18, vcc
	v_pk_mul_f32 v[118:119], v[2:3], v[4:5]
	v_pk_add_f32 v[2:3], v[114:115], s[4:5] op_sel_hi:[0,1]
	v_cmp_lt_f32_e32 vcc, 0, v2
	s_mov_b32 s4, 0xc2d40000
	s_mov_b32 s5, 0xc2d60000
	v_cndmask_b32_e64 v4, -v97, v101, vcc
	v_cmp_lt_f32_e32 vcc, 0, v3
	v_mul_f32_e32 v4, v2, v4
	v_exp_f32_e32 v4, v4
	v_cndmask_b32_e64 v5, -v97, v101, vcc
	v_mul_f32_e32 v5, v3, v5
	v_exp_f32_e32 v5, v5
	v_cmp_neq_f32_e32 vcc, 0, v3
	v_cvt_pk_bf16_f32 v18, v167, v168
	v_cvt_pk_bf16_f32 v117, v118, v119
	v_cndmask_b32_e32 v3, 2.0, v5, vcc
	v_cmp_neq_f32_e32 vcc, 0, v2
	s_nop 1
	v_cndmask_b32_e32 v2, 2.0, v4, vcc
	v_pk_mul_f32 v[120:121], v[2:3], v[6:7]
	v_pk_add_f32 v[2:3], v[114:115], s[4:5] op_sel_hi:[0,1]
	v_cmp_lt_f32_e32 vcc, 0, v2
	s_mov_b32 s4, 0xc2e00000
	s_mov_b32 s5, 0xc2e20000
	v_cndmask_b32_e64 v4, -v97, v101, vcc
	v_cmp_lt_f32_e32 vcc, 0, v3
	v_mul_f32_e32 v4, v2, v4
	v_exp_f32_e32 v4, v4
	v_cndmask_b32_e64 v5, -v97, v101, vcc
	v_mul_f32_e32 v5, v3, v5
	v_exp_f32_e32 v5, v5
	v_cmp_neq_f32_e32 vcc, 0, v3
	v_cvt_pk_bf16_f32 v118, v120, v121
	s_nop 0
	v_cndmask_b32_e32 v3, 2.0, v5, vcc
	v_cmp_neq_f32_e32 vcc, 0, v2
	s_nop 1
	v_cndmask_b32_e32 v2, 2.0, v4, vcc
	v_pk_mul_f32 v[124:125], v[2:3], v[8:9]
	v_pk_add_f32 v[2:3], v[114:115], s[4:5] op_sel_hi:[0,1]
	v_cmp_lt_f32_e32 vcc, 0, v2
	s_mov_b32 s4, 0xc2e40000
	s_mov_b32 s5, 0xc2e60000
	v_cndmask_b32_e64 v4, -v97, v101, vcc
	v_cmp_lt_f32_e32 vcc, 0, v3
	v_mul_f32_e32 v4, v2, v4
	v_exp_f32_e32 v4, v4
	v_cndmask_b32_e64 v5, -v97, v101, vcc
	v_mul_f32_e32 v5, v3, v5
	v_exp_f32_e32 v5, v5
	v_cmp_neq_f32_e32 vcc, 0, v3
	v_cvt_pk_bf16_f32 v119, v124, v125
	s_nop 0
	v_cndmask_b32_e32 v3, 2.0, v5, vcc
	v_cmp_neq_f32_e32 vcc, 0, v2
	s_nop 1
	v_cndmask_b32_e32 v2, 2.0, v4, vcc
	v_pk_mul_f32 v[108:109], v[2:3], v[10:11]
	v_pk_add_f32 v[2:3], v[114:115], s[4:5] op_sel_hi:[0,1]
	v_cmp_lt_f32_e32 vcc, 0, v2
	s_mov_b32 s4, 0xc2f00000
	s_mov_b32 s5, 0xc2f20000
	v_cndmask_b32_e64 v4, -v97, v101, vcc
	v_cmp_lt_f32_e32 vcc, 0, v3
	v_mul_f32_e32 v4, v2, v4
	v_exp_f32_e32 v4, v4
	v_cndmask_b32_e64 v5, -v97, v101, vcc
	v_mul_f32_e32 v5, v3, v5
	v_exp_f32_e32 v5, v5
	v_cmp_neq_f32_e32 vcc, 0, v3
	v_cvt_pk_bf16_f32 v108, v108, v109
	s_nop 0
	v_cndmask_b32_e32 v3, 2.0, v5, vcc
	v_cmp_neq_f32_e32 vcc, 0, v2
	s_nop 1
	v_cndmask_b32_e32 v2, 2.0, v4, vcc
	v_pk_mul_f32 v[110:111], v[2:3], v[12:13]
	v_pk_add_f32 v[2:3], v[114:115], s[4:5] op_sel_hi:[0,1]
	v_cmp_lt_f32_e32 vcc, 0, v2
	s_mov_b32 s4, 0xc2f40000
	s_mov_b32 s5, 0xc2f60000
	v_cndmask_b32_e64 v4, -v97, v101, vcc
	v_cmp_lt_f32_e32 vcc, 0, v3
	v_mul_f32_e32 v4, v2, v4
	v_exp_f32_e32 v4, v4
	v_cndmask_b32_e64 v5, -v97, v101, vcc
	v_mul_f32_e32 v5, v3, v5
	v_exp_f32_e32 v5, v5
	v_cmp_neq_f32_e32 vcc, 0, v3
	v_cvt_pk_bf16_f32 v109, v110, v111
	s_nop 0
	v_cndmask_b32_e32 v3, 2.0, v5, vcc
	v_cmp_neq_f32_e32 vcc, 0, v2
	s_nop 1
	v_cndmask_b32_e32 v2, 2.0, v4, vcc
	v_pk_mul_f32 v[112:113], v[2:3], v[14:15]
	v_pk_add_f32 v[2:3], v[114:115], s[4:5] op_sel_hi:[0,1]
	v_cmp_lt_f32_e32 vcc, 0, v2
	v_cvt_pk_bf16_f32 v110, v112, v113
	v_lshlrev_b32_e32 v112, 16, v71
	v_cndmask_b32_e64 v4, -v97, v101, vcc
	v_cmp_lt_f32_e32 vcc, 0, v3
	v_mul_f32_e32 v4, v2, v4
	v_exp_f32_e32 v4, v4
	v_cndmask_b32_e64 v5, -v97, v101, vcc
	v_mul_f32_e32 v5, v3, v5
	v_exp_f32_e32 v5, v5
	v_cmp_neq_f32_e32 vcc, 0, v3
	v_and_b32_e32 v113, 0xffff0000, v71
	v_and_b32_e32 v71, 0xffff0000, v68
	v_cndmask_b32_e32 v3, 2.0, v5, vcc
	v_cmp_neq_f32_e32 vcc, 0, v2
	s_nop 1
	v_cndmask_b32_e32 v2, 2.0, v4, vcc
	v_pk_mul_f32 v[114:115], v[2:3], v[16:17]
	ds_read_b128 v[2:5], v166
	ds_read_b128 v[168:171], v166 offset:32
	ds_read_b128 v[22:25], v166 offset:8704
	s_waitcnt lgkmcnt(2)
	v_mfma_f32_32x32x16_bf16 v[2:17], v[2:5], v[18:21], 0
	v_cvt_pk_bf16_f32 v111, v114, v115
	v_cmp_ne_u64_e32 vcc, 0, v[106:107]
	v_lshlrev_b32_e32 v114, 16, v70
	v_and_b32_e32 v115, 0xffff0000, v70
	v_lshlrev_b32_e32 v70, 16, v68
	s_waitcnt lgkmcnt(0)
	v_mfma_f32_32x32x16_bf16 v[34:49], v[22:25], v[18:21], 0
	ds_read_b128 v[22:25], v166 offset:17408
	v_mfma_f32_32x32x16_bf16 v[2:17], v[168:171], v[184:187], v[2:17]
	s_waitcnt lgkmcnt(0)
	v_mfma_f32_32x32x16_bf16 v[50:65], v[22:25], v[18:21], 0
	ds_read_b128 v[22:25], v166 offset:26112
	ds_read_b128 v[172:175], v166 offset:26144
	ds_read_b128 v[176:179], v166 offset:17440
	ds_read_b128 v[180:183], v166 offset:8736
	ds_read_b128 v[148:151], v166 offset:64
	ds_read_b128 v[156:159], v166 offset:96
	s_waitcnt lgkmcnt(1)
	v_mfma_f32_32x32x16_bf16 v[2:17], v[148:151], v[140:143], v[2:17]
	ds_read_b128 v[148:151], v166 offset:8768
	v_mfma_f32_32x32x16_bf16 v[34:49], v[180:183], v[184:187], v[34:49]
	s_waitcnt lgkmcnt(0)
; __device__ __forceinline__ float ex2(float x) { return __builtin_amdgcn_exp2f(x); }
; #define MFMA32(a, b, c) __builtin_amdgcn_mfma_f32_32x32x16_bf16((a), (b), (c), 0, 0, 0)
; __device__ __forceinline__ void phase_r3(bf16_t* P1, const bf16_t* ST, const bf16_t* CT, const float* dfw, const float* dbw, const float* gn, uchar* lds, bool with_ctx, bool nostore = false) {
;     ...
;         f32x16 oT[4] = {};
; #pragma unroll
;         for (int kk = 0; kk < 8; ++kk) {
;             const int jb = kk >> 1, r0 = 8 * (kk & 1);
;             const bf16x8 pf = pack8(sT[jb][r0], sT[jb][r0 + 1], sT[jb][r0 + 2], sT[jb][r0 + 3], sT[jb][r0 + 4], sT[jb][r0 + 5], sT[jb][r0 + 6], sT[jb][r0 + 7]);
; #pragma unroll
;             for (int dvb = 0; dvb < 4; ++dvb) { const bf16x8 av = *(const bf16x8*)(Tv + (dvb * 32 + l32) * TS + (16 * kk + 8 * hi) * 2); oT[dvb] = MFMA32(av, pf, oT[dvb]); }
;             if (kk & 1) asm volatile("" ::: "memory");
;         }
; #pragma unroll
;         for (int dir = 0; dir < 2; ++dir) {
;             const bf16_t* sp = dir ? stb : stf;
;     ...
;             sp = nullptr;
;     ...
;             if (sp) {
;                 const float dec = dir ? ex2(lgb * (float)(128 - il)) : ex2(lgf * (float)(il + 1));
; #pragma unroll
;                 for (int s = 0; s < 4; ++s) {
;                     const bf16x8 qd = __builtin_bit_cast(bf16x8, scale8(__builtin_bit_cast(u32x4, qf[s]), dec));
	v_mfma_f32_32x32x16_bf16 v[34:49], v[148:151], v[140:143], v[34:49]
	ds_read_b128 v[148:151], v166 offset:17472
	v_mfma_f32_32x32x16_bf16 v[50:65], v[176:179], v[184:187], v[50:65]
	v_mfma_f32_32x32x16_bf16 v[18:33], v[22:25], v[18:21], 0
	s_waitcnt lgkmcnt(0)
	v_mfma_f32_32x32x16_bf16 v[50:65], v[148:151], v[140:143], v[50:65]
	ds_read_b128 v[148:151], v166 offset:26176
	v_mfma_f32_32x32x16_bf16 v[18:33], v[172:175], v[184:187], v[18:33]
	s_waitcnt lgkmcnt(0)
	v_mfma_f32_32x32x16_bf16 v[18:33], v[148:151], v[140:143], v[18:33]
	ds_read_b128 v[140:143], v166 offset:26208
	ds_read_b128 v[148:151], v166 offset:17504
	ds_read_b128 v[168:171], v166 offset:8800
	v_mfma_f32_32x32x16_bf16 v[2:17], v[156:159], v[126:129], v[2:17]
	s_waitcnt lgkmcnt(0)
	v_mfma_f32_32x32x16_bf16 v[34:49], v[168:171], v[126:129], v[34:49]
	v_mfma_f32_32x32x16_bf16 v[50:65], v[148:151], v[126:129], v[50:65]
	v_cvt_pk_bf16_f32 v150, v122, v123
	v_cvt_pk_bf16_f32 v151, v130, v131
	v_mfma_f32_32x32x16_bf16 v[18:33], v[140:143], v[126:129], v[18:33]
	v_cvt_pk_bf16_f32 v126, v138, v139
	ds_read_b128 v[138:141], v166 offset:128
	ds_read_b128 v[142:145], v166 offset:160
	v_cvt_pk_bf16_f32 v127, v146, v147
	v_cvt_pk_bf16_f32 v128, v154, v155
	v_cvt_pk_bf16_f32 v129, v160, v161
	s_waitcnt lgkmcnt(1)
	s_nop 0
	v_mfma_f32_32x32x16_bf16 v[2:17], v[138:141], v[126:129], v[2:17]
	ds_read_b128 v[138:141], v166 offset:8832
	s_waitcnt lgkmcnt(0)
	v_mfma_f32_32x32x16_bf16 v[34:49], v[138:141], v[126:129], v[34:49]
	ds_read_b128 v[138:141], v166 offset:17536
	s_waitcnt lgkmcnt(0)
	v_mfma_f32_32x32x16_bf16 v[50:65], v[138:141], v[126:129], v[50:65]
	ds_read_b128 v[138:141], v166 offset:26240
	s_waitcnt lgkmcnt(0)
	v_mfma_f32_32x32x16_bf16 v[18:33], v[138:141], v[126:129], v[18:33]
	ds_read_b128 v[126:129], v166 offset:26272
	ds_read_b128 v[138:141], v166 offset:17568
	ds_read_b128 v[146:149], v166 offset:8864
	v_mfma_f32_32x32x16_bf16 v[2:17], v[142:145], v[150:153], v[2:17]
	s_waitcnt lgkmcnt(2)
	v_mfma_f32_32x32x16_bf16 v[18:33], v[126:129], v[150:153], v[18:33]
	ds_read_b128 v[120:123], v166 offset:192
	ds_read_b128 v[124:127], v166 offset:224
	s_waitcnt lgkmcnt(1)
	v_mfma_f32_32x32x16_bf16 v[2:17], v[120:123], v[116:119], v[2:17]
	ds_read_b128 v[120:123], v166 offset:8896
	v_mfma_f32_32x32x16_bf16 v[34:49], v[146:149], v[150:153], v[34:49]
	s_waitcnt lgkmcnt(0)
	v_mfma_f32_32x32x16_bf16 v[34:49], v[120:123], v[116:119], v[34:49]
	ds_read_b128 v[120:123], v166 offset:17600
	v_mfma_f32_32x32x16_bf16 v[50:65], v[138:141], v[150:153], v[50:65]
	s_waitcnt lgkmcnt(0)
	v_mfma_f32_32x32x16_bf16 v[50:65], v[120:123], v[116:119], v[50:65]
	ds_read_b128 v[120:123], v166 offset:26304
	s_waitcnt lgkmcnt(0)
	v_mfma_f32_32x32x16_bf16 v[18:33], v[120:123], v[116:119], v[18:33]
	ds_read_b128 v[116:119], v166 offset:26336
	ds_read_b128 v[120:123], v166 offset:17632
	ds_read_b128 v[128:131], v166 offset:8928
	v_mfma_f32_32x32x16_bf16 v[2:17], v[124:127], v[108:111], v[2:17]
	v_lshlrev_b32_e32 v126, 16, v81
	v_and_b32_e32 v127, 0xffff0000, v81
	v_lshlrev_b32_e32 v124, 1, v84
	s_waitcnt lgkmcnt(0)
	v_mfma_f32_32x32x16_bf16 v[34:49], v[128:131], v[108:111], v[34:49]
	v_lshlrev_b32_e32 v130, 16, v79
	v_and_b32_e32 v131, 0xffff0000, v79
	v_lshlrev_b32_e32 v128, 16, v80
	v_and_b32_e32 v129, 0xffff0000, v80
	v_lshlrev_b32_e32 v80, 1, v88
	v_mfma_f32_32x32x16_bf16 v[50:65], v[120:123], v[108:111], v[50:65]
	v_lshlrev_b32_e32 v122, 16, v74
	v_and_b32_e32 v123, 0xffff0000, v74
	v_lshlrev_b32_e32 v120, 16, v75
	v_and_b32_e32 v121, 0xffff0000, v75
	v_lshlrev_b32_e32 v74, 16, v66
	v_and_b32_e32 v75, 0xffff0000, v66
	v_lshlrev_b32_e32 v66, 16, v69
	v_mfma_f32_32x32x16_bf16 v[18:33], v[116:119], v[108:111], v[18:33]
	v_lshlrev_b32_e32 v108, 1, v90
	v_lshlrev_b32_e32 v118, 16, v76
	v_and_b32_e32 v119, 0xffff0000, v76
	v_lshlrev_b32_e32 v116, 16, v77
	v_and_b32_e32 v117, 0xffff0000, v77
	v_lshlrev_b32_e32 v110, 16, v72
	v_and_b32_e32 v111, 0xffff0000, v72
	v_lshlrev_b32_e32 v76, 16, v73
	v_and_b32_e32 v77, 0xffff0000, v73
	v_lshlrev_b32_e32 v72, 16, v67
	v_and_b32_e32 v73, 0xffff0000, v67
	v_and_b32_e32 v67, 0xffff0000, v69
	s_and_saveexec_b64 s[40:41], vcc
	s_cbranch_execz .LBB0_1200
; __device__ __forceinline__ float ex2(float x) { return __builtin_amdgcn_exp2f(x); }
; #define MFMA32(a, b, c) __builtin_amdgcn_mfma_f32_32x32x16_bf16((a), (b), (c), 0, 0, 0)
; __device__ __forceinline__ void phase_r3(bf16_t* P1, const bf16_t* ST, const bf16_t* CT, const float* dfw, const float* dbw, const float* gn, uchar* lds, bool with_ctx, bool nostore = false) {
;     ...
;             if (sp) {
;                 const float dec = dir ? ex2(lgb * (float)(128 - il)) : ex2(lgf * (float)(il + 1));
; #pragma unroll
;                 for (int s = 0; s < 4; ++s) {
;                     const bf16x8 qd = __builtin_bit_cast(bf16x8, scale8(__builtin_bit_cast(u32x4, qf[s]), dec));
; #pragma unroll
;                     for (int dvb = 0; dvb < 4; ++dvb) { const bf16x8 av = *(const bf16x8*)(sp + (dvb * 32 + l32) * 64 + 16 * s + 8 * hi); oT[dvb] = MFMA32(av, qd, oT[dvb]); }
;                     if (s & 1) asm volatile("" ::: "memory");
;                 }
;             }
	v_add_u32_e32 v68, 1, v95
	v_cvt_f32_i32_e32 v68, v68
	v_lshl_add_u64 v[134:135], v[106:107], 0, v[98:99]
	v_mov_b32_e32 v125, v1
	v_mov_b32_e32 v79, v1
	v_mul_f32_e32 v68, v101, v68
	v_exp_f32_e32 v68, v68
	v_mov_b32_e32 v81, v1
	v_mov_b32_e32 v109, v1
	v_lshl_add_u64 v[144:145], v[134:135], 0, 32
	v_pk_mul_f32 v[106:107], v[68:69], v[132:133] op_sel_hi:[0,1]
	v_cvt_pk_bf16_f32 v136, v106, v107
	v_pk_mul_f32 v[106:107], v[68:69], v[130:131] op_sel_hi:[0,1]
	v_cvt_pk_bf16_f32 v137, v106, v107
	v_pk_mul_f32 v[106:107], v[68:69], v[128:129] op_sel_hi:[0,1]
	v_cvt_pk_bf16_f32 v138, v106, v107
	v_pk_mul_f32 v[106:107], v[68:69], v[126:127] op_sel_hi:[0,1]
	v_cvt_pk_bf16_f32 v139, v106, v107
	v_lshl_add_u64 v[106:107], v[134:135], 0, v[124:125]
	global_load_dwordx4 v[140:143], v[106:107], off
	v_pk_mul_f32 v[152:153], v[68:69], v[122:123] op_sel_hi:[0,1]
	v_pk_mul_f32 v[154:155], v[68:69], v[120:121] op_sel_hi:[0,1]
	v_cvt_pk_bf16_f32 v152, v152, v153
	v_cvt_pk_bf16_f32 v153, v154, v155
	v_pk_mul_f32 v[154:155], v[68:69], v[118:119] op_sel_hi:[0,1]
	v_pk_mul_f32 v[156:157], v[68:69], v[116:117] op_sel_hi:[0,1]
	v_cvt_pk_bf16_f32 v154, v154, v155
	v_cvt_pk_bf16_f32 v155, v156, v157
	s_mov_b64 s[4:5], 0x60
	s_waitcnt vmcnt(0)
	v_mfma_f32_32x32x16_bf16 v[2:17], v[140:143], v[136:139], v[2:17]
	v_lshl_add_u64 v[140:141], v[134:135], 0, v[78:79]
	global_load_dwordx4 v[140:143], v[140:141], off
	s_waitcnt vmcnt(0)
	v_mfma_f32_32x32x16_bf16 v[34:49], v[140:143], v[136:139], v[34:49]
	v_lshl_add_u64 v[140:141], v[134:135], 0, v[80:81]
	global_load_dwordx4 v[140:143], v[140:141], off
	s_waitcnt vmcnt(0)
	v_mfma_f32_32x32x16_bf16 v[50:65], v[140:143], v[136:139], v[50:65]
	v_lshl_add_u64 v[140:141], v[134:135], 0, v[108:109]
	global_load_dwordx4 v[140:143], v[140:141], off
	s_waitcnt vmcnt(0)
	v_mfma_f32_32x32x16_bf16 v[18:33], v[140:143], v[136:139], v[18:33]
	v_lshl_add_u64 v[136:137], v[144:145], 0, v[108:109]
	global_load_dwordx4 v[136:139], v[136:137], off
	v_lshl_add_u64 v[140:141], v[144:145], 0, v[80:81]
	global_load_dwordx4 v[140:143], v[140:141], off
	v_lshl_add_u64 v[144:145], v[144:145], 0, v[78:79]
	global_load_dwordx4 v[144:147], v[144:145], off
	s_nop 0
	global_load_dwordx4 v[148:151], v[106:107], off offset:32
	s_waitcnt vmcnt(1)
	v_mfma_f32_32x32x16_bf16 v[34:49], v[144:147], v[152:155], v[34:49]
	v_lshl_add_u64 v[144:145], v[134:135], 0, 64
	v_mfma_f32_32x32x16_bf16 v[18:33], v[136:139], v[152:155], v[18:33]
	v_mul_f32_e64 v136, v68, v114
	v_mul_f32_e64 v137, v68, v115
	v_mul_f32_e64 v138, v68, v112
	v_mul_f32_e64 v139, v68, v113
	v_cvt_pk_bf16_f32 v136, v136, v137
	v_cvt_pk_bf16_f32 v137, v138, v139
	v_pk_mul_f32 v[138:139], v[68:69], v[110:111] op_sel_hi:[0,1]
	v_cvt_pk_bf16_f32 v138, v138, v139
	v_mfma_f32_32x32x16_bf16 v[50:65], v[140:143], v[152:155], v[50:65]
	v_mul_f32_e64 v140, v68, v76
	v_mul_f32_e64 v141, v68, v77
	v_cvt_pk_bf16_f32 v139, v140, v141
	global_load_dwordx4 v[140:143], v[106:107], off offset:64
	s_waitcnt vmcnt(1)
	v_mfma_f32_32x32x16_bf16 v[2:17], v[148:151], v[152:155], v[2:17]
	s_waitcnt vmcnt(0)
	v_mfma_f32_32x32x16_bf16 v[2:17], v[140:143], v[136:139], v[2:17]
	v_lshl_add_u64 v[140:141], v[144:145], 0, v[78:79]
	global_load_dwordx4 v[140:143], v[140:141], off
	s_waitcnt vmcnt(0)
	v_mfma_f32_32x32x16_bf16 v[34:49], v[140:143], v[136:139], v[34:49]
	v_lshl_add_u64 v[140:141], v[144:145], 0, v[80:81]
	global_load_dwordx4 v[140:143], v[140:141], off
	s_waitcnt vmcnt(0)
	v_mfma_f32_32x32x16_bf16 v[50:65], v[140:143], v[136:139], v[50:65]
	v_lshl_add_u64 v[140:141], v[144:145], 0, v[108:109]
	global_load_dwordx4 v[140:143], v[140:141], off
	s_waitcnt vmcnt(0)
	v_mfma_f32_32x32x16_bf16 v[18:33], v[140:143], v[136:139], v[18:33]
	v_lshl_add_u64 v[142:143], v[134:135], 0, s[4:5]
	v_lshl_add_u64 v[134:135], v[142:143], 0, v[108:109]
	v_lshl_add_u64 v[138:139], v[142:143], 0, v[80:81]
	global_load_dwordx4 v[134:137], v[134:135], off
	v_lshl_add_u64 v[142:143], v[142:143], 0, v[78:79]
	global_load_dwordx4 v[138:141], v[138:139], off
	s_nop 0
	global_load_dwordx4 v[142:145], v[142:143], off
	s_nop 0
	global_load_dwordx4 v[146:149], v[106:107], off offset:96
	v_pk_mul_f32 v[106:107], v[68:69], v[74:75] op_sel_hi:[0,1]
	v_cvt_pk_bf16_f32 v150, v106, v107
	v_pk_mul_f32 v[106:107], v[68:69], v[72:73] op_sel_hi:[0,1]
	v_cvt_pk_bf16_f32 v151, v106, v107
	v_pk_mul_f32 v[106:107], v[68:69], v[70:71] op_sel_hi:[0,1]
	v_pk_mul_f32 v[68:69], v[68:69], v[66:67] op_sel_hi:[0,1]
	v_cvt_pk_bf16_f32 v152, v106, v107
	v_cvt_pk_bf16_f32 v153, v68, v69
	s_waitcnt vmcnt(1)
	s_nop 0
	v_mfma_f32_32x32x16_bf16 v[34:49], v[142:145], v[150:153], v[34:49]
	s_waitcnt vmcnt(0)
	v_mfma_f32_32x32x16_bf16 v[2:17], v[146:149], v[150:153], v[2:17]
	v_mfma_f32_32x32x16_bf16 v[50:65], v[138:141], v[150:153], v[50:65]
	v_mfma_f32_32x32x16_bf16 v[18:33], v[134:137], v[150:153], v[18:33]

; __device__ __forceinline__ void phase_r3(bf16_t* P1, const bf16_t* ST, const bf16_t* CT, const float* dfw, const float* dbw, const float* gn, uchar* lds, bool with_ctx, bool nostore = false) {
;     ...
;         float sm = 0.f;
; #pragma unroll
;         for (int dvb = 0; dvb < 4; ++dvb)
; #pragma unroll
;             for (int r = 0; r < 16; ++r) sm += oT[dvb][r];
;         sm += __shfl_xor(sm, 32); const float mu = sm * (1.f / 128.f);
;         float sq = 0.f;
; #pragma unroll
;         for (int dvb = 0; dvb < 4; ++dvb)
; #pragma unroll
;             for (int r = 0; r < 16; ++r) { const float d = oT[dvb][r] - mu; sq += d * d; }
;         sq += __shfl_xor(sq, 32); const float rstd = 1.f / sqrtf(sq * (1.f / 128.f) + EPSN);
.LBB0_1202:
	s_or_b64 exec, exec, s[40:41]
	s_nop 9
	v_add_f32_e32 v66, 0, v2
	v_add_f32_e32 v66, v3, v66
	v_add_f32_e32 v66, v4, v66
	v_add_f32_e32 v66, v5, v66
	v_add_f32_e32 v66, v6, v66
	v_add_f32_e32 v66, v7, v66
	v_add_f32_e32 v66, v8, v66
	v_add_f32_e32 v66, v9, v66
	v_add_f32_e32 v66, v10, v66
	v_add_f32_e32 v66, v11, v66
	v_add_f32_e32 v66, v12, v66
	v_add_f32_e32 v66, v13, v66
	v_add_f32_e32 v66, v14, v66
	v_add_f32_e32 v66, v15, v66
	v_add_f32_e32 v66, v16, v66
	v_add_f32_e32 v66, v17, v66
	v_add_f32_e32 v66, v34, v66
	v_add_f32_e32 v66, v35, v66
	v_add_f32_e32 v66, v36, v66
	v_add_f32_e32 v66, v37, v66
	v_add_f32_e32 v66, v38, v66
	v_add_f32_e32 v66, v39, v66
	v_add_f32_e32 v66, v40, v66
	v_add_f32_e32 v66, v41, v66
	v_add_f32_e32 v66, v42, v66
	v_add_f32_e32 v66, v43, v66
	v_add_f32_e32 v66, v44, v66
	v_add_f32_e32 v66, v45, v66
	v_add_f32_e32 v66, v46, v66
	v_add_f32_e32 v66, v47, v66
	v_add_f32_e32 v66, v48, v66
	v_add_f32_e32 v66, v49, v66
	v_add_f32_e32 v66, v50, v66
	v_add_f32_e32 v66, v51, v66
	v_add_f32_e32 v66, v52, v66
	v_add_f32_e32 v66, v53, v66
	v_add_f32_e32 v66, v54, v66
	v_add_f32_e32 v66, v55, v66
	v_add_f32_e32 v66, v56, v66
	v_add_f32_e32 v66, v57, v66
	v_add_f32_e32 v66, v58, v66
	v_add_f32_e32 v66, v59, v66
	v_add_f32_e32 v66, v60, v66
	v_add_f32_e32 v66, v61, v66
	v_add_f32_e32 v66, v62, v66
	v_add_f32_e32 v66, v63, v66
	v_add_f32_e32 v66, v64, v66
	v_add_f32_e32 v66, v65, v66
	v_add_f32_e32 v66, v18, v66
	v_add_f32_e32 v66, v19, v66
	v_add_f32_e32 v66, v20, v66
	v_add_f32_e32 v66, v21, v66
	v_add_f32_e32 v66, v22, v66
	v_add_f32_e32 v66, v23, v66
	v_add_f32_e32 v66, v24, v66
	v_add_f32_e32 v66, v25, v66
	v_add_f32_e32 v66, v26, v66
	v_add_f32_e32 v66, v27, v66
	v_add_f32_e32 v66, v28, v66
	v_add_f32_e32 v66, v29, v66
	v_and_b32_e32 v68, 64, v210
	v_add_f32_e32 v66, v30, v66
	v_xor_b32_e32 v67, 32, v210
	v_add_u32_e32 v68, 64, v68
	v_add_f32_e32 v66, v31, v66
	v_cmp_lt_i32_e32 vcc, v67, v68
	v_add_f32_e32 v66, v32, v66
	v_add_f32_e32 v66, v33, v66
	v_cndmask_b32_e32 v67, v210, v67, vcc
	v_lshlrev_b32_e32 v97, 2, v67
	ds_bpermute_b32 v67, v97, v66
	s_mov_b32 s4, 0xf800000
	s_waitcnt lgkmcnt(0)
	v_add_f32_e32 v66, v66, v67
	v_mul_f32_e32 v120, 0x3c000000, v66
	v_pk_add_f32 v[2:3], v[2:3], v[120:121] op_sel_hi:[1,0] neg_lo:[0,1] neg_hi:[0,1]
	v_pk_add_f32 v[118:119], v[4:5], v[120:121] op_sel_hi:[1,0] neg_lo:[0,1] neg_hi:[0,1]
	v_pk_add_f32 v[116:117], v[6:7], v[120:121] op_sel_hi:[1,0] neg_lo:[0,1] neg_hi:[0,1]
	v_pk_add_f32 v[114:115], v[8:9], v[120:121] op_sel_hi:[1,0] neg_lo:[0,1] neg_hi:[0,1]
	v_pk_add_f32 v[112:113], v[10:11], v[120:121] op_sel_hi:[1,0] neg_lo:[0,1] neg_hi:[0,1]
	v_pk_add_f32 v[110:111], v[12:13], v[120:121] op_sel_hi:[1,0] neg_lo:[0,1] neg_hi:[0,1]
	v_pk_add_f32 v[108:109], v[14:15], v[120:121] op_sel_hi:[1,0] neg_lo:[0,1] neg_hi:[0,1]
	v_pk_add_f32 v[106:107], v[16:17], v[120:121] op_sel_hi:[1,0] neg_lo:[0,1] neg_hi:[0,1]
	v_pk_add_f32 v[104:105], v[34:35], v[120:121] op_sel_hi:[1,0] neg_lo:[0,1] neg_hi:[0,1]
	v_pk_add_f32 v[80:81], v[36:37], v[120:121] op_sel_hi:[1,0] neg_lo:[0,1] neg_hi:[0,1]
	v_pk_add_f32 v[78:79], v[38:39], v[120:121] op_sel_hi:[1,0] neg_lo:[0,1] neg_hi:[0,1]
	v_pk_add_f32 v[76:77], v[40:41], v[120:121] op_sel_hi:[1,0] neg_lo:[0,1] neg_hi:[0,1]
	v_pk_add_f32 v[74:75], v[42:43], v[120:121] op_sel_hi:[1,0] neg_lo:[0,1] neg_hi:[0,1]
	v_pk_add_f32 v[72:73], v[44:45], v[120:121] op_sel_hi:[1,0] neg_lo:[0,1] neg_hi:[0,1]
	v_pk_add_f32 v[70:71], v[46:47], v[120:121] op_sel_hi:[1,0] neg_lo:[0,1] neg_hi:[0,1]
	v_pk_add_f32 v[68:69], v[48:49], v[120:121] op_sel_hi:[1,0] neg_lo:[0,1] neg_hi:[0,1]
	v_pk_add_f32 v[66:67], v[50:51], v[120:121] op_sel_hi:[1,0] neg_lo:[0,1] neg_hi:[0,1]
	v_pk_add_f32 v[50:51], v[52:53], v[120:121] op_sel_hi:[1,0] neg_lo:[0,1] neg_hi:[0,1]
	v_pk_add_f32 v[48:49], v[54:55], v[120:121] op_sel_hi:[1,0] neg_lo:[0,1] neg_hi:[0,1]
	v_pk_add_f32 v[46:47], v[56:57], v[120:121] op_sel_hi:[1,0] neg_lo:[0,1] neg_hi:[0,1]
	v_pk_add_f32 v[44:45], v[58:59], v[120:121] op_sel_hi:[1,0] neg_lo:[0,1] neg_hi:[0,1]
	v_pk_add_f32 v[42:43], v[60:61], v[120:121] op_sel_hi:[1,0] neg_lo:[0,1] neg_hi:[0,1]
	v_pk_add_f32 v[40:41], v[62:63], v[120:121] op_sel_hi:[1,0] neg_lo:[0,1] neg_hi:[0,1]
	v_pk_add_f32 v[38:39], v[64:65], v[120:121] op_sel_hi:[1,0] neg_lo:[0,1] neg_hi:[0,1]
	v_pk_add_f32 v[36:37], v[18:19], v[120:121] op_sel_hi:[1,0] neg_lo:[0,1] neg_hi:[0,1]
	v_pk_add_f32 v[34:35], v[20:21], v[120:121] op_sel_hi:[1,0] neg_lo:[0,1] neg_hi:[0,1]
	v_pk_add_f32 v[20:21], v[22:23], v[120:121] op_sel_hi:[1,0] neg_lo:[0,1] neg_hi:[0,1]
	v_pk_add_f32 v[18:19], v[24:25], v[120:121] op_sel_hi:[1,0] neg_lo:[0,1] neg_hi:[0,1]
	v_pk_add_f32 v[16:17], v[26:27], v[120:121] op_sel_hi:[1,0] neg_lo:[0,1] neg_hi:[0,1]
	v_pk_add_f32 v[14:15], v[28:29], v[120:121] op_sel_hi:[1,0] neg_lo:[0,1] neg_hi:[0,1]
	v_pk_add_f32 v[10:11], v[30:31], v[120:121] op_sel_hi:[1,0] neg_lo:[0,1] neg_hi:[0,1]
	v_pk_add_f32 v[8:9], v[32:33], v[120:121] op_sel_hi:[1,0] neg_lo:[0,1] neg_hi:[0,1]
	v_pk_mul_f32 v[120:121], v[2:3], v[2:3]
	v_pk_mul_f32 v[122:123], v[118:119], v[118:119]
	v_lshl_add_u64 v[12:13], v[0:1], 2, v[92:93]
	v_add_f32_e32 v0, v120, v121
	v_add_f32_e32 v0, v122, v0
	v_pk_mul_f32 v[124:125], v[116:117], v[116:117]
	v_add_f32_e32 v0, v123, v0
	v_add_f32_e32 v0, v124, v0
	v_pk_mul_f32 v[126:127], v[114:115], v[114:115]
	v_add_f32_e32 v0, v125, v0
	v_add_f32_e32 v0, v126, v0
	v_pk_mul_f32 v[128:129], v[112:113], v[112:113]
	v_add_f32_e32 v0, v127, v0
	v_add_f32_e32 v0, v128, v0
	v_pk_mul_f32 v[130:131], v[110:111], v[110:111]
	v_add_f32_e32 v0, v129, v0
	v_add_f32_e32 v0, v130, v0
; __device__ __forceinline__ unsigned pk2(float lo, float hi) { f32x2_t v = {lo, hi}; bf16x2_t b = __builtin_convertvector(v, bf16x2_t); return __builtin_bit_cast(unsigned, b); }
; __device__ __forceinline__ void phase_r3(bf16_t* P1, const bf16_t* ST, const bf16_t* CT, const float* dfw, const float* dbw, const float* gn, uchar* lds, bool with_ctx, bool nostore = false) {
;     ...
;             for (int r = 0; r < 16; ++r) { const float d = oT[dvb][r] - mu; sq += d * d; }
;         sq += __shfl_xor(sq, 32); const float rstd = 1.f / sqrtf(sq * (1.f / 128.f) + EPSN);
;         const float* gp = gn + h * 128;
; #pragma unroll
;         for (int dvb = 0; dvb < 4; ++dvb)
; #pragma unroll
;             for (int rq = 0; rq < 4; ++rq) { const int dv = 32 * dvb + 8 * rq + 4 * hi; const f32x4 g = *(const f32x4*)(gp + dv) * (1.f / LOG2E);
;                 u32x2 w; w.x = pk2((oT[dvb][4 * rq] - mu) * rstd * g.x, (oT[dvb][4 * rq + 1] - mu) * rstd * g.y); w.y = pk2((oT[dvb][4 * rq + 2] - mu) * rstd * g.z, (oT[dvb][4 * rq + 3] - mu) * rstd * g.w);
;                 if (!nostore || w.x == 0x12345678u) *(u32x2*)(vp + (size_t)il * P1W + dv) = w; if (rq == 3) asm volatile("" ::: "memory"); }
	v_pk_mul_f32 v[132:133], v[108:109], v[108:109]
	v_add_f32_e32 v0, v131, v0
	v_add_f32_e32 v0, v132, v0
	v_pk_mul_f32 v[134:135], v[106:107], v[106:107]
	v_add_f32_e32 v0, v133, v0
	v_add_f32_e32 v0, v134, v0
	v_pk_mul_f32 v[136:137], v[104:105], v[104:105]
	v_add_f32_e32 v0, v135, v0
	v_add_f32_e32 v0, v136, v0
	v_pk_mul_f32 v[138:139], v[80:81], v[80:81]
	v_add_f32_e32 v0, v137, v0
	v_add_f32_e32 v0, v138, v0
	v_pk_mul_f32 v[140:141], v[78:79], v[78:79]
	v_add_f32_e32 v0, v139, v0
	global_load_dwordx4 v[4:7], v[12:13], off
	global_load_dwordx4 v[194:197], v[12:13], off offset:32
	global_load_dwordx4 v[198:201], v[12:13], off offset:64
	global_load_dwordx4 v[202:205], v[12:13], off offset:96
	global_load_dwordx4 v[212:215], v[12:13], off offset:128
	global_load_dwordx4 v[220:223], v[12:13], off offset:160
	global_load_dwordx4 v[224:227], v[12:13], off offset:192
	global_load_dwordx4 v[228:231], v[12:13], off offset:224
	global_load_dwordx4 v[232:235], v[12:13], off offset:256
	global_load_dwordx4 v[236:239], v[12:13], off offset:288
	global_load_dwordx4 v[240:243], v[12:13], off offset:320
	global_load_dwordx4 v[244:247], v[12:13], off offset:352
	v_add_f32_e32 v0, v140, v0
	v_pk_mul_f32 v[142:143], v[76:77], v[76:77]
	v_add_f32_e32 v0, v141, v0
	v_add_f32_e32 v0, v142, v0
	v_pk_mul_f32 v[144:145], v[74:75], v[74:75]
	v_add_f32_e32 v0, v143, v0
	v_add_f32_e32 v0, v144, v0
	v_pk_mul_f32 v[146:147], v[72:73], v[72:73]
	v_add_f32_e32 v0, v145, v0
	v_add_f32_e32 v0, v146, v0
	v_pk_mul_f32 v[148:149], v[70:71], v[70:71]
	v_add_f32_e32 v0, v147, v0
	v_add_f32_e32 v0, v148, v0
	v_pk_mul_f32 v[150:151], v[68:69], v[68:69]
	v_add_f32_e32 v0, v149, v0
	v_add_f32_e32 v0, v150, v0
	v_pk_mul_f32 v[152:153], v[66:67], v[66:67]
	v_add_f32_e32 v0, v151, v0
	v_add_f32_e32 v0, v152, v0
	v_pk_mul_f32 v[52:53], v[50:51], v[50:51]
	v_add_f32_e32 v0, v153, v0
	v_add_f32_e32 v0, v52, v0
	v_pk_mul_f32 v[54:55], v[48:49], v[48:49]
	v_add_f32_e32 v0, v53, v0
	v_add_f32_e32 v0, v54, v0
	v_pk_mul_f32 v[56:57], v[46:47], v[46:47]
	v_add_f32_e32 v0, v55, v0
	v_add_f32_e32 v0, v56, v0
	v_pk_mul_f32 v[58:59], v[44:45], v[44:45]
	v_add_f32_e32 v0, v57, v0
	v_add_f32_e32 v0, v58, v0
	v_pk_mul_f32 v[60:61], v[42:43], v[42:43]
	v_add_f32_e32 v0, v59, v0
	v_add_f32_e32 v0, v60, v0
	v_pk_mul_f32 v[62:63], v[40:41], v[40:41]
	v_add_f32_e32 v0, v61, v0
	v_add_f32_e32 v0, v62, v0
	v_pk_mul_f32 v[64:65], v[38:39], v[38:39]
	v_add_f32_e32 v0, v63, v0
	v_add_f32_e32 v0, v64, v0
	v_pk_mul_f32 v[154:155], v[36:37], v[36:37]
	v_add_f32_e32 v0, v65, v0
	v_add_f32_e32 v0, v154, v0
	v_pk_mul_f32 v[156:157], v[34:35], v[34:35]
	v_add_f32_e32 v0, v155, v0
	v_add_f32_e32 v0, v156, v0
	v_pk_mul_f32 v[22:23], v[20:21], v[20:21]
	v_add_f32_e32 v0, v157, v0
	v_add_f32_e32 v0, v22, v0
	v_pk_mul_f32 v[24:25], v[18:19], v[18:19]
	v_add_f32_e32 v0, v23, v0
	v_add_f32_e32 v0, v24, v0
	v_pk_mul_f32 v[26:27], v[16:17], v[16:17]
	v_add_f32_e32 v0, v25, v0
	v_add_f32_e32 v0, v26, v0
	v_pk_mul_f32 v[28:29], v[14:15], v[14:15]
	v_add_f32_e32 v0, v27, v0
	v_add_f32_e32 v0, v28, v0
	v_pk_mul_f32 v[30:31], v[10:11], v[10:11]
	v_add_f32_e32 v0, v29, v0
	v_add_f32_e32 v0, v30, v0
	v_pk_mul_f32 v[32:33], v[8:9], v[8:9]
	v_add_f32_e32 v0, v31, v0
	v_add_f32_e32 v0, v32, v0
	v_add_f32_e32 v0, v33, v0
	ds_bpermute_b32 v22, v97, v0
	s_waitcnt lgkmcnt(0)
	v_add_f32_e32 v0, v0, v22
	v_fmamk_f32 v0, v0, 0x3c000000, v207
	v_mul_f32_e32 v22, 0x4f800000, v0
	v_cmp_gt_f32_e32 vcc, s4, v0
	s_waitcnt vmcnt(0)
	v_pk_mul_f32 v[4:5], v[4:5], s[12:13] op_sel_hi:[1,0]
	v_cndmask_b32_e32 v0, v0, v22, vcc
	v_sqrt_f32_e32 v22, v0
	s_nop 0
	v_add_u32_e32 v23, -1, v22
	v_fma_f32 v24, -v23, v22, v0
	v_cmp_ge_f32_e64 s[40:41], 0, v24
	v_add_u32_e32 v24, 1, v22
	s_nop 0
	v_cndmask_b32_e64 v23, v22, v23, s[40:41]
	v_fma_f32 v22, -v24, v22, v0
	v_cmp_lt_f32_e64 s[40:41], 0, v22
	s_nop 1
	v_cndmask_b32_e64 v22, v23, v24, s[40:41]
	v_mul_f32_e32 v23, 0x37800000, v22
	v_cndmask_b32_e32 v22, v22, v23, vcc
	v_cmp_class_f32_e32 vcc, v0, v208
	s_nop 1
	v_cndmask_b32_e32 v0, v22, v0, vcc
	v_div_scale_f32 v24, s[4:5], v0, v0, 1.0
	v_rcp_f32_e32 v25, v24
	v_mad_i64_i32 v[22:23], s[4:5], v95, s16, 0
	v_readlane_b32 s4, v252, 43
	v_fma_f32 v26, -v24, v25, 1.0
	v_fmac_f32_e32 v25, v26, v25
	v_div_scale_f32 v26, vcc, 1.0, v0, 1.0
	v_mul_f32_e32 v27, v26, v25
	v_fma_f32 v28, -v24, v27, v26
	v_fmac_f32_e32 v27, v28, v25
	v_fma_f32 v24, -v24, v27, v26
	v_div_fmas_f32 v24, v24, v25, v27
	v_div_fixup_f32 v24, v24, v0, 1.0
	v_mov_b32_e32 v25, v24
	v_pk_mul_f32 v[2:3], v[2:3], v[24:25] op_sel_hi:[1,0]
	v_readlane_b32 s5, v252, 44
	v_pk_mul_f32 v[2:3], v[4:5], v[2:3]
	s_xor_b64 s[40:41], s[4:5], -1
	v_cvt_pk_bf16_f32 v2, v2, v3
	v_cmp_eq_u32_e32 vcc, s65, v2
	v_lshl_add_u64 v[22:23], v[102:103], 0, v[22:23]
	s_or_b64 s[8:9], s[40:41], vcc
	v_lshlrev_b32_e32 v0, 1, v82
	s_and_saveexec_b64 s[4:5], s[8:9]
	s_cbranch_execz .LBB0_1204
	v_pk_mul_f32 v[4:5], v[6:7], s[12:13] op_sel_hi:[1,0]
	v_pk_mul_f32 v[6:7], v[118:119], v[24:25]
	s_nop 0
	v_pk_mul_f32 v[4:5], v[4:5], v[6:7]
	s_nop 0
	v_cvt_pk_bf16_f32 v3, v4, v5
	v_lshl_add_u64 v[4:5], v[22:23], 0, v[0:1]
	global_store_dwordx2 v[4:5], v[2:3], off offset:2048
.LBB0_1204:
	s_or_b64 exec, exec, s[4:5]
	v_pk_mul_f32 v[6:7], v[116:117], v[24:25]
	s_nop 0
	v_pk_mul_f32 v[2:3], v[194:195], s[12:13] op_sel_hi:[1,0]
	s_nop 0
	v_pk_mul_f32 v[2:3], v[6:7], v[2:3]
	s_nop 0
	v_cvt_pk_bf16_f32 v2, v2, v3
	v_cmp_eq_u32_e32 vcc, s65, v2
	s_or_b64 s[8:9], s[40:41], vcc
	s_and_saveexec_b64 s[4:5], s[8:9]
	s_cbranch_execz .LBB0_1206
	v_pk_mul_f32 v[4:5], v[196:197], s[12:13] op_sel_hi:[1,0]
	v_pk_mul_f32 v[6:7], v[114:115], v[24:25]
	s_nop 0
	v_pk_mul_f32 v[4:5], v[6:7], v[4:5]
	s_nop 0
	v_cvt_pk_bf16_f32 v3, v4, v5
	v_lshl_add_u64 v[4:5], v[22:23], 0, v[0:1]
	global_store_dwordx2 v[4:5], v[2:3], off offset:2064
; __device__ __forceinline__ unsigned pk2(float lo, float hi) { f32x2_t v = {lo, hi}; bf16x2_t b = __builtin_convertvector(v, bf16x2_t); return __builtin_bit_cast(unsigned, b); }
; __device__ __forceinline__ void phase_r3(bf16_t* P1, const bf16_t* ST, const bf16_t* CT, const float* dfw, const float* dbw, const float* gn, uchar* lds, bool with_ctx, bool nostore = false) {
;     ...
;         for (int dvb = 0; dvb < 4; ++dvb)
; #pragma unroll
;             for (int rq = 0; rq < 4; ++rq) { const int dv = 32 * dvb + 8 * rq + 4 * hi; const f32x4 g = *(const f32x4*)(gp + dv) * (1.f / LOG2E);
;                 u32x2 w; w.x = pk2((oT[dvb][4 * rq] - mu) * rstd * g.x, (oT[dvb][4 * rq + 1] - mu) * rstd * g.y); w.y = pk2((oT[dvb][4 * rq + 2] - mu) * rstd * g.z, (oT[dvb][4 * rq + 3] - mu) * rstd * g.w);
;                 if (!nostore || w.x == 0x12345678u) *(u32x2*)(vp + (size_t)il * P1W + dv) = w; if (rq == 3) asm volatile("" ::: "memory"); }
.LBB0_1206:
	s_or_b64 exec, exec, s[4:5]
	global_load_dwordx4 v[194:197], v[12:13], off offset:384
	v_pk_mul_f32 v[6:7], v[112:113], v[24:25]
	s_nop 0
	v_pk_mul_f32 v[2:3], v[198:199], s[12:13] op_sel_hi:[1,0]
	s_nop 0
	v_pk_mul_f32 v[2:3], v[6:7], v[2:3]
	s_nop 0
	v_cvt_pk_bf16_f32 v2, v2, v3
	v_cmp_eq_u32_e32 vcc, s65, v2
	s_or_b64 s[8:9], s[40:41], vcc
	s_and_saveexec_b64 s[4:5], s[8:9]
	s_cbranch_execz .LBB0_1208
	v_pk_mul_f32 v[4:5], v[200:201], s[12:13] op_sel_hi:[1,0]
	v_pk_mul_f32 v[6:7], v[110:111], v[24:25]
	s_nop 0
	v_pk_mul_f32 v[4:5], v[6:7], v[4:5]
	s_nop 0
	v_cvt_pk_bf16_f32 v3, v4, v5
	v_lshl_add_u64 v[4:5], v[22:23], 0, v[0:1]
	global_store_dwordx2 v[4:5], v[2:3], off offset:2080
.LBB0_1208:
	s_or_b64 exec, exec, s[4:5]
	global_load_dwordx4 v[198:201], v[12:13], off offset:416
	v_pk_mul_f32 v[6:7], v[108:109], v[24:25]
	s_nop 0
	v_pk_mul_f32 v[2:3], v[202:203], s[12:13] op_sel_hi:[1,0]
	s_nop 0
	v_pk_mul_f32 v[2:3], v[6:7], v[2:3]
	s_nop 0
	v_cvt_pk_bf16_f32 v2, v2, v3
	v_cmp_eq_u32_e32 vcc, s65, v2
	s_or_b64 s[8:9], s[40:41], vcc
	s_and_saveexec_b64 s[4:5], s[8:9]
	s_cbranch_execz .LBB0_1210
	v_pk_mul_f32 v[4:5], v[204:205], s[12:13] op_sel_hi:[1,0]
	v_pk_mul_f32 v[6:7], v[106:107], v[24:25]
	s_nop 0
	v_pk_mul_f32 v[4:5], v[6:7], v[4:5]
	s_nop 0
	v_cvt_pk_bf16_f32 v3, v4, v5
	v_lshl_add_u64 v[4:5], v[22:23], 0, v[0:1]
	global_store_dwordx2 v[4:5], v[2:3], off offset:2096
.LBB0_1210:
	s_or_b64 exec, exec, s[4:5]
	global_load_dwordx4 v[202:205], v[12:13], off offset:448
	v_pk_mul_f32 v[6:7], v[104:105], v[24:25]
	s_nop 0
	v_pk_mul_f32 v[2:3], v[212:213], s[12:13] op_sel_hi:[1,0]
	s_nop 0
	v_pk_mul_f32 v[2:3], v[6:7], v[2:3]
	s_nop 0
	v_cvt_pk_bf16_f32 v2, v2, v3
	v_cmp_eq_u32_e32 vcc, s65, v2
	s_or_b64 s[8:9], s[40:41], vcc
	s_and_saveexec_b64 s[4:5], s[8:9]
	s_cbranch_execz .LBB0_1212
	v_pk_mul_f32 v[4:5], v[214:215], s[12:13] op_sel_hi:[1,0]
	v_pk_mul_f32 v[6:7], v[80:81], v[24:25]
	s_nop 0
	v_pk_mul_f32 v[4:5], v[6:7], v[4:5]
	s_nop 0
	v_cvt_pk_bf16_f32 v3, v4, v5
	v_mov_b32_e32 v4, v0
	v_mov_b32_e32 v5, v1
	v_lshl_add_u64 v[4:5], v[22:23], 0, v[4:5]
	global_store_dwordx2 v[4:5], v[2:3], off offset:2112
.LBB0_1212:
	s_or_b64 exec, exec, s[4:5]
	global_load_dwordx4 v[212:215], v[12:13], off offset:480
	v_pk_mul_f32 v[6:7], v[78:79], v[24:25]
	s_nop 0
	v_pk_mul_f32 v[2:3], v[220:221], s[12:13] op_sel_hi:[1,0]
	s_nop 0
	v_pk_mul_f32 v[2:3], v[6:7], v[2:3]
	s_nop 0
	v_cvt_pk_bf16_f32 v2, v2, v3
	v_cmp_eq_u32_e32 vcc, s65, v2
	s_or_b64 s[8:9], s[40:41], vcc
	s_and_saveexec_b64 s[4:5], s[8:9]
	s_cbranch_execz .LBB0_1214
	v_pk_mul_f32 v[4:5], v[222:223], s[12:13] op_sel_hi:[1,0]
	v_pk_mul_f32 v[6:7], v[76:77], v[24:25]
	s_nop 0
	v_pk_mul_f32 v[4:5], v[6:7], v[4:5]
	s_nop 0
	v_cvt_pk_bf16_f32 v3, v4, v5
	v_mov_b32_e32 v4, v0
	v_mov_b32_e32 v5, v1
	v_lshl_add_u64 v[4:5], v[22:23], 0, v[4:5]
	global_store_dwordx2 v[4:5], v[2:3], off offset:2128
.LBB0_1214:
	s_or_b64 exec, exec, s[4:5]
	v_pk_mul_f32 v[6:7], v[74:75], v[24:25]
	s_nop 0
	v_pk_mul_f32 v[2:3], v[224:225], s[12:13] op_sel_hi:[1,0]
	s_nop 0
	v_pk_mul_f32 v[2:3], v[6:7], v[2:3]
	s_nop 0
	v_cvt_pk_bf16_f32 v2, v2, v3
	v_cmp_eq_u32_e32 vcc, s65, v2
	s_or_b64 s[8:9], s[40:41], vcc
	s_and_saveexec_b64 s[4:5], s[8:9]
	s_cbranch_execz .LBB0_1216
	v_pk_mul_f32 v[4:5], v[226:227], s[12:13] op_sel_hi:[1,0]
	v_pk_mul_f32 v[6:7], v[72:73], v[24:25]
	s_nop 0
	v_pk_mul_f32 v[4:5], v[6:7], v[4:5]
	s_nop 0
	v_cvt_pk_bf16_f32 v3, v4, v5
	v_mov_b32_e32 v4, v0
	v_mov_b32_e32 v5, v1
	v_lshl_add_u64 v[4:5], v[22:23], 0, v[4:5]
	global_store_dwordx2 v[4:5], v[2:3], off offset:2144
.LBB0_1216:
	s_or_b64 exec, exec, s[4:5]
	v_pk_mul_f32 v[6:7], v[70:71], v[24:25]
	s_nop 0
	v_pk_mul_f32 v[2:3], v[228:229], s[12:13] op_sel_hi:[1,0]
	s_nop 0
	v_pk_mul_f32 v[2:3], v[6:7], v[2:3]
	s_nop 0
	v_cvt_pk_bf16_f32 v2, v2, v3
	v_cmp_eq_u32_e32 vcc, s65, v2
	s_or_b64 s[8:9], s[40:41], vcc
	s_and_saveexec_b64 s[4:5], s[8:9]
	s_cbranch_execz .LBB0_1218
	v_pk_mul_f32 v[4:5], v[230:231], s[12:13] op_sel_hi:[1,0]
	v_pk_mul_f32 v[6:7], v[68:69], v[24:25]
	s_nop 0
	v_pk_mul_f32 v[4:5], v[6:7], v[4:5]
	s_nop 0
	v_cvt_pk_bf16_f32 v3, v4, v5
	v_mov_b32_e32 v4, v0
	v_mov_b32_e32 v5, v1
	v_lshl_add_u64 v[4:5], v[22:23], 0, v[4:5]
	global_store_dwordx2 v[4:5], v[2:3], off offset:2160
.LBB0_1218:
	s_or_b64 exec, exec, s[4:5]
	v_pk_mul_f32 v[6:7], v[66:67], v[24:25]
	s_nop 0
	v_pk_mul_f32 v[2:3], v[232:233], s[12:13] op_sel_hi:[1,0]
	s_nop 0
	v_pk_mul_f32 v[2:3], v[6:7], v[2:3]
	s_nop 0
	v_cvt_pk_bf16_f32 v2, v2, v3
	v_cmp_eq_u32_e32 vcc, s65, v2
	s_or_b64 s[8:9], s[40:41], vcc
	s_and_saveexec_b64 s[4:5], s[8:9]
	s_cbranch_execz .LBB0_1220
	v_pk_mul_f32 v[4:5], v[234:235], s[12:13] op_sel_hi:[1,0]
	v_pk_mul_f32 v[6:7], v[50:51], v[24:25]
	s_nop 0
	v_pk_mul_f32 v[4:5], v[6:7], v[4:5]
	s_nop 0
	v_cvt_pk_bf16_f32 v3, v4, v5
	v_mov_b32_e32 v4, v0
	v_mov_b32_e32 v5, v1
	v_lshl_add_u64 v[4:5], v[22:23], 0, v[4:5]
	global_store_dwordx2 v[4:5], v[2:3], off offset:2176
; __device__ __forceinline__ unsigned pk2(float lo, float hi) { f32x2_t v = {lo, hi}; bf16x2_t b = __builtin_convertvector(v, bf16x2_t); return __builtin_bit_cast(unsigned, b); }
; __device__ __forceinline__ void phase_r3(bf16_t* P1, const bf16_t* ST, const bf16_t* CT, const float* dfw, const float* dbw, const float* gn, uchar* lds, bool with_ctx, bool nostore = false) {
;     ...
;         for (int dvb = 0; dvb < 4; ++dvb)
; #pragma unroll
;             for (int rq = 0; rq < 4; ++rq) { const int dv = 32 * dvb + 8 * rq + 4 * hi; const f32x4 g = *(const f32x4*)(gp + dv) * (1.f / LOG2E);
;                 u32x2 w; w.x = pk2((oT[dvb][4 * rq] - mu) * rstd * g.x, (oT[dvb][4 * rq + 1] - mu) * rstd * g.y); w.y = pk2((oT[dvb][4 * rq + 2] - mu) * rstd * g.z, (oT[dvb][4 * rq + 3] - mu) * rstd * g.w);
;                 if (!nostore || w.x == 0x12345678u) *(u32x2*)(vp + (size_t)il * P1W + dv) = w; if (rq == 3) asm volatile("" ::: "memory"); }
;         __syncthreads();
;     }
.LBB0_1220:
	s_or_b64 exec, exec, s[4:5]
	v_pk_mul_f32 v[6:7], v[48:49], v[24:25]
	s_nop 0
	v_pk_mul_f32 v[2:3], v[236:237], s[12:13] op_sel_hi:[1,0]
	s_nop 0
	v_pk_mul_f32 v[2:3], v[6:7], v[2:3]
	s_nop 0
	v_cvt_pk_bf16_f32 v2, v2, v3
	v_cmp_eq_u32_e32 vcc, s65, v2
	s_or_b64 s[8:9], s[40:41], vcc
	s_and_saveexec_b64 s[4:5], s[8:9]
	s_cbranch_execz .LBB0_1222
	v_pk_mul_f32 v[4:5], v[238:239], s[12:13] op_sel_hi:[1,0]
	v_pk_mul_f32 v[6:7], v[46:47], v[24:25]
	s_nop 0
	v_pk_mul_f32 v[4:5], v[6:7], v[4:5]
	s_nop 0
	v_cvt_pk_bf16_f32 v3, v4, v5
	v_mov_b32_e32 v4, v0
	v_mov_b32_e32 v5, v1
	v_lshl_add_u64 v[4:5], v[22:23], 0, v[4:5]
	global_store_dwordx2 v[4:5], v[2:3], off offset:2192
.LBB0_1222:
	s_or_b64 exec, exec, s[4:5]
	v_pk_mul_f32 v[6:7], v[44:45], v[24:25]
	s_nop 0
	v_pk_mul_f32 v[2:3], v[240:241], s[12:13] op_sel_hi:[1,0]
	s_nop 0
	v_pk_mul_f32 v[2:3], v[6:7], v[2:3]
	s_nop 0
	v_cvt_pk_bf16_f32 v2, v2, v3
	v_cmp_eq_u32_e32 vcc, s65, v2
	s_or_b64 s[8:9], s[40:41], vcc
	s_and_saveexec_b64 s[4:5], s[8:9]
	s_cbranch_execz .LBB0_1224
	v_pk_mul_f32 v[4:5], v[242:243], s[12:13] op_sel_hi:[1,0]
	v_pk_mul_f32 v[6:7], v[42:43], v[24:25]
	s_nop 0
	v_pk_mul_f32 v[4:5], v[6:7], v[4:5]
	s_nop 0
	v_cvt_pk_bf16_f32 v3, v4, v5
	v_mov_b32_e32 v4, v0
	v_mov_b32_e32 v5, v1
	v_lshl_add_u64 v[4:5], v[22:23], 0, v[4:5]
	global_store_dwordx2 v[4:5], v[2:3], off offset:2208
.LBB0_1224:
	s_or_b64 exec, exec, s[4:5]
	v_pk_mul_f32 v[6:7], v[40:41], v[24:25]
	s_nop 0
	v_pk_mul_f32 v[2:3], v[244:245], s[12:13] op_sel_hi:[1,0]
	s_nop 0
	v_pk_mul_f32 v[2:3], v[6:7], v[2:3]
	s_nop 0
	v_cvt_pk_bf16_f32 v2, v2, v3
	v_cmp_eq_u32_e32 vcc, s65, v2
	s_or_b64 s[8:9], s[40:41], vcc
	s_and_saveexec_b64 s[4:5], s[8:9]
	s_cbranch_execz .LBB0_1226
	v_pk_mul_f32 v[4:5], v[246:247], s[12:13] op_sel_hi:[1,0]
	v_pk_mul_f32 v[6:7], v[38:39], v[24:25]
	s_nop 0
	v_pk_mul_f32 v[4:5], v[6:7], v[4:5]
	s_nop 0
	v_cvt_pk_bf16_f32 v3, v4, v5
	v_mov_b32_e32 v4, v0
	v_mov_b32_e32 v5, v1
	v_lshl_add_u64 v[4:5], v[22:23], 0, v[4:5]
	global_store_dwordx2 v[4:5], v[2:3], off offset:2224
.LBB0_1226:
	s_or_b64 exec, exec, s[4:5]
	v_pk_mul_f32 v[6:7], v[36:37], v[24:25]
	s_waitcnt vmcnt(3)
	v_pk_mul_f32 v[2:3], v[194:195], s[12:13] op_sel_hi:[1,0]
	s_nop 0
	v_pk_mul_f32 v[2:3], v[6:7], v[2:3]
	s_nop 0
	v_cvt_pk_bf16_f32 v2, v2, v3
	v_cmp_eq_u32_e32 vcc, s65, v2
	s_or_b64 s[8:9], s[40:41], vcc
	s_and_saveexec_b64 s[4:5], s[8:9]
	s_cbranch_execz .LBB0_1228
	v_pk_mul_f32 v[4:5], v[196:197], s[12:13] op_sel_hi:[1,0]
	v_pk_mul_f32 v[6:7], v[34:35], v[24:25]
	s_nop 0
	v_pk_mul_f32 v[4:5], v[6:7], v[4:5]
	s_nop 0
	v_cvt_pk_bf16_f32 v3, v4, v5
	v_mov_b32_e32 v4, v0
	v_mov_b32_e32 v5, v1
	v_lshl_add_u64 v[4:5], v[22:23], 0, v[4:5]
	global_store_dwordx2 v[4:5], v[2:3], off offset:2240
.LBB0_1228:
	s_or_b64 exec, exec, s[4:5]
	v_pk_mul_f32 v[6:7], v[20:21], v[24:25]
	s_waitcnt vmcnt(2)
	v_pk_mul_f32 v[2:3], v[198:199], s[12:13] op_sel_hi:[1,0]
	s_nop 0
	v_pk_mul_f32 v[2:3], v[6:7], v[2:3]
	s_nop 0
	v_cvt_pk_bf16_f32 v2, v2, v3
	v_cmp_eq_u32_e32 vcc, s65, v2
	s_or_b64 s[8:9], s[40:41], vcc
	s_and_saveexec_b64 s[4:5], s[8:9]
	s_cbranch_execz .LBB0_1230
	v_pk_mul_f32 v[4:5], v[200:201], s[12:13] op_sel_hi:[1,0]
	v_pk_mul_f32 v[6:7], v[18:19], v[24:25]
	s_nop 0
	v_pk_mul_f32 v[4:5], v[6:7], v[4:5]
	s_nop 0
	v_cvt_pk_bf16_f32 v3, v4, v5
	v_mov_b32_e32 v4, v0
	v_mov_b32_e32 v5, v1
	v_lshl_add_u64 v[4:5], v[22:23], 0, v[4:5]
	global_store_dwordx2 v[4:5], v[2:3], off offset:2256
.LBB0_1230:
	s_or_b64 exec, exec, s[4:5]
	v_pk_mul_f32 v[6:7], v[16:17], v[24:25]
	s_waitcnt vmcnt(1)
	v_pk_mul_f32 v[2:3], v[202:203], s[12:13] op_sel_hi:[1,0]
	s_nop 0
	v_pk_mul_f32 v[2:3], v[6:7], v[2:3]
	s_nop 0
	v_cvt_pk_bf16_f32 v2, v2, v3
	v_cmp_eq_u32_e32 vcc, s65, v2
	s_or_b64 s[8:9], s[40:41], vcc
	s_and_saveexec_b64 s[4:5], s[8:9]
	s_cbranch_execz .LBB0_1232
	v_pk_mul_f32 v[4:5], v[204:205], s[12:13] op_sel_hi:[1,0]
	v_pk_mul_f32 v[6:7], v[14:15], v[24:25]
	s_nop 0
	v_pk_mul_f32 v[4:5], v[6:7], v[4:5]
	s_nop 0
	v_cvt_pk_bf16_f32 v3, v4, v5
	v_mov_b32_e32 v4, v0
	v_mov_b32_e32 v5, v1
	v_lshl_add_u64 v[4:5], v[22:23], 0, v[4:5]
	global_store_dwordx2 v[4:5], v[2:3], off offset:2272
.LBB0_1232:
	s_or_b64 exec, exec, s[4:5]
	v_pk_mul_f32 v[6:7], v[10:11], v[24:25]
	s_waitcnt vmcnt(0)
	v_pk_mul_f32 v[2:3], v[212:213], s[12:13] op_sel_hi:[1,0]
	s_nop 0
	v_pk_mul_f32 v[2:3], v[6:7], v[2:3]
	s_nop 0
	v_cvt_pk_bf16_f32 v2, v2, v3
	v_cmp_eq_u32_e32 vcc, s65, v2
	s_or_b64 s[8:9], s[40:41], vcc
	s_and_saveexec_b64 s[4:5], s[8:9]
	s_cbranch_execz .LBB0_1193
	v_pk_mul_f32 v[4:5], v[214:215], s[12:13] op_sel_hi:[1,0]
	v_pk_mul_f32 v[6:7], v[8:9], v[24:25]
	s_nop 0
	v_pk_mul_f32 v[4:5], v[6:7], v[4:5]
	s_nop 0
	v_cvt_pk_bf16_f32 v3, v4, v5
	v_mov_b32_e32 v4, v0
	v_mov_b32_e32 v5, v1
	v_lshl_add_u64 v[4:5], v[22:23], 0, v[4:5]
	global_store_dwordx2 v[4:5], v[2:3], off offset:2288
	s_branch .LBB0_1193
